# combo15 + row-pass 1/2 butterflies xor16/xor32 via v_permlane16/32_swap (no ds_bpermute left in those reductions)
# baseline (speedup 1.0000x reference)
; #define LAS __attribute__((address_space(3)))
; __device__ __forceinline__ void wave_sum2(float& a, float& b) {
; #pragma unroll
;     for (int o = 1; o < 64; o <<= 1) { const float ta = __shfl_xor(a, o), tb = __shfl_xor(b, o); a += ta; b += tb; }
; }
; __device__ __forceinline__ void row_pass(const Params& P, int l, int mode, LAS float* pl) {
;     ...
;         if (mode != 0) {
;             float s[2], q[2];
; #pragma unroll
;             for (int r = 0; r < 2; ++r) { const LAS float* gm = pl + mv[r] * DM; s[r] = 0.f; q[r] = 0.f;
; #pragma unroll
;                 for (int j = 0; j < 4; ++j) { const f32x4 g = *(const LAS f32x4*)(gm + 4 * lane + 256 * j); v[r][j] = v[r][j] * ALPHA + g * yv[r][j];
;                     s[r] += (v[r][j][0] + v[r][j][1]) + (v[r][j][2] + v[r][j][3]); const f32x4 sq = v[r][j] * v[r][j]; q[r] += (sq[0] + sq[1]) + (sq[2] + sq[3]); } }
;             wave_sum2(s[0], s[1]); wave_sum2(q[0], q[1]);
.LBB0_1042:
	s_mul_i32 s4, s19, 0x2100
	s_add_i32 s10, s4, s10
	s_mul_i32 s4, s18, 0x2100
	s_add_i32 s14, s4, s14
	s_ashr_i32 s15, s14, 31
	s_ashr_i32 s11, s10, 31
	s_lshl_b64 s[4:5], s[14:15], 12
	s_lshl_b32 s18, s18, 12
	s_and_b64 s[0:1], s[0:1], exec
	s_cselect_b32 s0, s18, 0x2000
	v_add_u32_e32 v127, s0, v15
	ds_read_b128 v[128:131], v127
	ds_read_b128 v[140:143], v127 offset:1024
	s_mov_b32 s20, 0x3fd744fd
	s_lshl_b32 s18, s19, 12
	s_and_b64 s[0:1], exec, s[16:17]
	s_waitcnt lgkmcnt(1)
	v_pk_mul_f32 v[72:73], v[130:131], v[72:73]
	v_pk_mul_f32 v[70:71], v[128:129], v[70:71]
	v_pk_fma_f32 v[56:57], v[56:57], s[20:21], v[72:73] op_sel_hi:[1,0,1]
	v_pk_fma_f32 v[54:55], v[54:55], s[20:21], v[70:71] op_sel_hi:[1,0,1]
	v_pk_mul_f32 v[70:71], v[56:57], v[56:57]
	s_waitcnt lgkmcnt(0)
	v_pk_mul_f32 v[76:77], v[142:143], v[76:77]
	v_add_f32_e32 v0, v70, v71
	v_pk_mul_f32 v[70:71], v[140:141], v[74:75]
	v_pk_fma_f32 v[48:49], v[48:49], s[20:21], v[76:77] op_sel_hi:[1,0,1]
	v_pk_fma_f32 v[46:47], v[46:47], s[20:21], v[70:71] op_sel_hi:[1,0,1]
	ds_read_b128 v[70:73], v127 offset:2048
	ds_read_b128 v[74:77], v127 offset:3072
	v_pk_mul_f32 v[132:133], v[54:55], v[54:55]
	v_add_f32_e32 v129, v54, v55
	v_add_f32_e32 v131, v56, v57
	v_pk_mul_f32 v[142:143], v[46:47], v[46:47]
	s_waitcnt lgkmcnt(1)
	v_pk_mul_f32 v[72:73], v[72:73], v[84:85]
	v_pk_mul_f32 v[70:71], v[70:71], v[82:83]
	v_mov_b32_e32 v128, v132
	v_mov_b32_e32 v130, v133
	v_pk_mul_f32 v[140:141], v[48:49], v[48:49]
	v_pk_fma_f32 v[42:43], v[42:43], s[20:21], v[70:71] op_sel_hi:[1,0,1]
	v_pk_fma_f32 v[44:45], v[44:45], s[20:21], v[72:73] op_sel_hi:[1,0,1]
	s_waitcnt lgkmcnt(0)
	v_pk_mul_f32 v[70:71], v[76:77], v[80:81]
	v_pk_mul_f32 v[72:73], v[74:75], v[78:79]
	v_pk_add_f32 v[78:79], v[128:129], v[130:131]
	v_mov_b32_e32 v80, v142
	v_mov_b32_e32 v81, v46
	v_mov_b32_e32 v128, v143
	v_mov_b32_e32 v129, v47
	v_pk_add_f32 v[80:81], v[80:81], v[128:129]
	v_mov_b32_e32 v128, v140
	v_mov_b32_e32 v129, v48
	v_mov_b32_e32 v130, v141
	v_mov_b32_e32 v131, v49
	v_pk_add_f32 v[128:129], v[128:129], v[130:131]
	v_pk_mul_f32 v[84:85], v[42:43], v[42:43]
	v_pk_add_f32 v[78:79], v[78:79], v[0:1]
	v_pk_add_f32 v[80:81], v[80:81], v[128:129]
	v_pk_mul_f32 v[82:83], v[44:45], v[44:45]
	v_pk_add_f32 v[78:79], v[78:79], v[80:81]
	v_mov_b32_e32 v80, v84
	v_mov_b32_e32 v81, v42
	v_mov_b32_e32 v84, v85
	v_mov_b32_e32 v85, v43
	v_pk_add_f32 v[80:81], v[80:81], v[84:85]
	v_mov_b32_e32 v84, v82
	v_mov_b32_e32 v85, v44
	v_mov_b32_e32 v82, v83
	v_mov_b32_e32 v83, v45
	v_pk_fma_f32 v[38:39], v[38:39], s[20:21], v[72:73] op_sel_hi:[1,0,1]
	v_pk_add_f32 v[82:83], v[84:85], v[82:83]
	v_pk_fma_f32 v[40:41], v[40:41], s[20:21], v[70:71] op_sel_hi:[1,0,1]
	v_pk_mul_f32 v[76:77], v[38:39], v[38:39]
	v_pk_add_f32 v[80:81], v[80:81], v[82:83]
	v_pk_mul_f32 v[74:75], v[40:41], v[40:41]
	v_pk_add_f32 v[78:79], v[78:79], v[80:81]
	v_mov_b32_e32 v80, v76
	v_mov_b32_e32 v81, v38
	v_mov_b32_e32 v76, v77
	v_mov_b32_e32 v77, v39
	v_pk_add_f32 v[76:77], v[80:81], v[76:77]
	v_mov_b32_e32 v80, v74
	v_mov_b32_e32 v81, v40
	v_mov_b32_e32 v74, v75
	v_mov_b32_e32 v75, v41
	s_cselect_b32 s0, s18, 0x2000
	v_pk_add_f32 v[74:75], v[80:81], v[74:75]
	v_add_u32_e32 v126, s0, v15
	v_pk_add_f32 v[74:75], v[76:77], v[74:75]
	ds_read_b128 v[70:73], v126
	v_pk_add_f32 v[78:79], v[78:79], v[74:75]
	s_nop 1
	v_mov_b32_dpp v81, v79 quad_perm:[1,0,3,2] row_mask:0xf bank_mask:0xf
	s_nop 1
	v_mov_b32_dpp v80, v78 quad_perm:[1,0,3,2] row_mask:0xf bank_mask:0xf
	ds_read_b128 v[74:77], v126 offset:1024
	s_waitcnt lgkmcnt(0)
	v_pk_mul_f32 v[72:73], v[72:73], v[88:89]
	v_pk_mul_f32 v[82:83], v[70:71], v[86:87]
	v_pk_fma_f32 v[70:71], v[68:69], s[20:21], v[72:73] op_sel_hi:[1,0,1]
	s_waitcnt lgkmcnt(0)
	v_pk_add_f32 v[68:69], v[78:79], v[80:81]
	s_nop 1
	v_mov_b32_dpp v79, v69 quad_perm:[2,3,0,1] row_mask:0xf bank_mask:0xf
	s_nop 1
	v_mov_b32_dpp v78, v68 quad_perm:[2,3,0,1] row_mask:0xf bank_mask:0xf
	v_pk_fma_f32 v[72:73], v[66:67], s[20:21], v[82:83] op_sel_hi:[1,0,1]
	s_waitcnt lgkmcnt(0)
	v_pk_mul_f32 v[76:77], v[76:77], v[92:93]
	v_pk_mul_f32 v[74:75], v[74:75], v[90:91]
	s_mov_b32 s16, 0x3a800000
	s_waitcnt lgkmcnt(0)
	v_pk_add_f32 v[66:67], v[68:69], v[78:79]
	s_nop 1
	v_mov_b32_dpp v69, v67 row_half_mirror row_mask:0xf bank_mask:0xf
	s_nop 1
	v_mov_b32_dpp v68, v66 row_half_mirror row_mask:0xf bank_mask:0xf
	v_pk_mul_f32 v[78:79], v[70:71], v[70:71]
	v_pk_fma_f32 v[74:75], v[62:63], s[20:21], v[74:75] op_sel_hi:[1,0,1]
	v_add_f32_e32 v140, v78, v79
	v_pk_fma_f32 v[78:79], v[64:65], s[20:21], v[76:77] op_sel_hi:[1,0,1]
	s_waitcnt lgkmcnt(0)
	v_pk_add_f32 v[66:67], v[66:67], v[68:69]
	s_nop 1
	v_mov_b32_dpp v69, v67 row_mirror row_mask:0xf bank_mask:0xf
	s_nop 1
	v_mov_b32_dpp v68, v66 row_mirror row_mask:0xf bank_mask:0xf
	ds_read_b128 v[62:65], v126 offset:2048
	v_pk_mul_f32 v[132:133], v[72:73], v[72:73]
	v_pk_mul_f32 v[144:145], v[74:75], v[74:75]
	v_add_f32_e32 v129, v72, v73
	s_waitcnt lgkmcnt(0)
	v_pk_add_f32 v[76:77], v[66:67], v[68:69]
	v_mov_b32_e32 v80, v76
	v_mov_b32_e32 v81, v77
	v_mov_b32_e32 v134, v76
	v_mov_b32_e32 v135, v77
	s_nop 1
	v_permlane16_swap_b32_e32 v80, v134
	v_permlane16_swap_b32_e32 v81, v135
	ds_read_b128 v[66:69], v126 offset:3072
	s_waitcnt lgkmcnt(0)
	v_pk_mul_f32 v[62:63], v[62:63], v[98:99]
	v_add_f32_e32 v131, v70, v71
	v_pk_mul_f32 v[142:143], v[78:79], v[78:79]
	s_waitcnt lgkmcnt(0)
	v_pk_add_f32 v[82:83], v[80:81], v[134:135]
	v_mov_b32_e32 v84, v82
	v_mov_b32_e32 v85, v83
	v_mov_b32_e32 v134, v82
	v_mov_b32_e32 v135, v83
	s_nop 1
	v_permlane32_swap_b32_e32 v84, v134
	v_permlane32_swap_b32_e32 v85, v135
	v_pk_fma_f32 v[76:77], v[58:59], s[20:21], v[62:63] op_sel_hi:[1,0,1]
	s_waitcnt lgkmcnt(0)
; #define LAS __attribute__((address_space(3)))
; __device__ __forceinline__ void wave_sum2(float& a, float& b) {
; #pragma unroll
;     for (int o = 1; o < 64; o <<= 1) { const float ta = __shfl_xor(a, o), tb = __shfl_xor(b, o); a += ta; b += tb; }
; }
; __device__ __forceinline__ void row_pass(const Params& P, int l, int mode, LAS float* pl) {
;     ...
;             wave_sum2(s[0], s[1]); wave_sum2(q[0], q[1]);
; #pragma unroll
;             for (int r = 0; r < 2; ++r) { const float mean = s[r] * (1.f / DM); const float var = fmaxf(q[r] * (1.f / DM) - mean * mean, 0.f); const float rstd = 1.f / sqrtf(var + LN_EPS);
; #pragma unroll
;                 for (int j = 0; j < 4; ++j) { const f32x4 g = *(const LAS f32x4*)(pl + 3072 + 4 * lane + 256 * j), bb = *(const LAS f32x4*)(pl + 4096 + 4 * lane + 256 * j); v[r][j] = (v[r][j] - mean) * rstd * g + bb; } }
	v_pk_mul_f32 v[66:67], v[66:67], v[94:95]
	v_pk_mul_f32 v[64:65], v[64:65], v[100:101]
	v_mov_b32_e32 v128, v132
	s_waitcnt lgkmcnt(0)
	v_pk_add_f32 v[62:63], v[84:85], v[134:135]
	v_pk_fma_f32 v[82:83], v[50:51], s[20:21], v[66:67] op_sel_hi:[1,0,1]
	v_pk_mul_f32 v[62:63], v[62:63], s[16:17] op_sel_hi:[1,0]
	s_mov_b32 s17, 0xf800000
	v_fma_f32 v0, -v63, v63, v62
	v_max_f32_e32 v0, 0, v0
	v_add_f32_e32 v0, 0x358637bd, v0
	v_mul_f32_e32 v62, 0x4f800000, v0
	v_cmp_gt_f32_e32 vcc, s17, v0
	v_mov_b32_e32 v130, v133
	v_mov_b32_e32 v98, v144
	v_cndmask_b32_e32 v0, v0, v62, vcc
	v_sqrt_f32_e32 v62, v0
	v_mov_b32_e32 v99, v74
	v_mov_b32_e32 v100, v145
	v_mov_b32_e32 v101, v75
	v_add_u32_e32 v50, -1, v62
	v_fma_f32 v51, -v50, v62, v0
	v_cmp_ge_f32_e64 s[0:1], 0, v51
	v_add_u32_e32 v51, 1, v62
	v_pk_fma_f32 v[80:81], v[60:61], s[20:21], v[64:65] op_sel_hi:[1,0,1]
	v_cndmask_b32_e64 v50, v62, v50, s[0:1]
	v_fma_f32 v62, -v51, v62, v0
	v_cmp_lt_f32_e64 s[0:1], 0, v62
	v_pk_mul_f32 v[64:65], v[68:69], v[96:97]
	v_pk_add_f32 v[68:69], v[128:129], v[130:131]
	v_cndmask_b32_e64 v50, v50, v51, s[0:1]
	v_mul_f32_e32 v51, 0x37800000, v50
	v_cndmask_b32_e32 v50, v50, v51, vcc
	v_cmp_class_f32_e32 vcc, v0, v217
	v_pk_add_f32 v[98:99], v[98:99], v[100:101]
	v_mov_b32_e32 v100, v142
	v_cndmask_b32_e32 v0, v50, v0, vcc
	v_div_scale_f32 v50, s[0:1], v0, v0, 1.0
	v_rcp_f32_e32 v51, v50
	v_mov_b32_e32 v101, v78
	v_mov_b32_e32 v128, v143
	v_mov_b32_e32 v129, v79
	v_mov_b32_e32 v141, v1
	v_pk_add_f32 v[100:101], v[100:101], v[128:129]
	v_pk_mul_f32 v[60:61], v[76:77], v[76:77]
	v_pk_add_f32 v[68:69], v[68:69], v[140:141]
	v_pk_add_f32 v[98:99], v[98:99], v[100:101]
	v_pk_mul_f32 v[58:59], v[80:81], v[80:81]
	v_pk_add_f32 v[68:69], v[68:69], v[98:99]
	v_mov_b32_e32 v98, v60
	v_mov_b32_e32 v99, v76
	v_mov_b32_e32 v60, v61
	v_mov_b32_e32 v61, v77
	v_pk_fma_f32 v[84:85], v[52:53], s[20:21], v[64:65] op_sel_hi:[1,0,1]
	v_fma_f32 v52, -v50, v51, 1.0
	v_pk_add_f32 v[60:61], v[98:99], v[60:61]
	v_mov_b32_e32 v98, v58
	v_mov_b32_e32 v99, v80
	v_mov_b32_e32 v58, v59
	v_mov_b32_e32 v59, v81
	v_pk_mul_f32 v[66:67], v[82:83], v[82:83]
	v_fmac_f32_e32 v51, v52, v51
	v_div_scale_f32 v52, vcc, 1.0, v0, 1.0
	v_pk_add_f32 v[58:59], v[98:99], v[58:59]
	v_pk_mul_f32 v[64:65], v[84:85], v[84:85]
	v_mul_f32_e32 v53, v52, v51
	v_pk_add_f32 v[58:59], v[60:61], v[58:59]
	v_mov_b32_e32 v60, v66
	v_mov_b32_e32 v61, v82
	v_mov_b32_e32 v66, v67
	v_mov_b32_e32 v67, v83
	v_fma_f32 v62, -v50, v53, v52
	v_pk_add_f32 v[60:61], v[60:61], v[66:67]
	v_mov_b32_e32 v66, v64
	v_mov_b32_e32 v67, v84
	v_mov_b32_e32 v64, v65
	v_mov_b32_e32 v65, v85
	v_fmac_f32_e32 v53, v62, v51
	v_pk_add_f32 v[64:65], v[66:67], v[64:65]
	v_fma_f32 v50, -v50, v53, v52
	v_pk_add_f32 v[58:59], v[68:69], v[58:59]
	v_pk_add_f32 v[60:61], v[60:61], v[64:65]
	v_div_fmas_f32 v50, v50, v51, v53
	v_pk_add_f32 v[58:59], v[58:59], v[60:61]
	v_div_fixup_f32 v0, v50, v0, 1.0
	v_sub_f32_e32 v51, v57, v63
	v_sub_f32_e32 v50, v56, v63
	v_sub_f32_e32 v53, v55, v63
	v_sub_f32_e32 v52, v54, v63
	s_nop 1
	v_mov_b32_dpp v61, v59 quad_perm:[1,0,3,2] row_mask:0xf bank_mask:0xf
	s_nop 1
	v_mov_b32_dpp v60, v58 quad_perm:[1,0,3,2] row_mask:0xf bank_mask:0xf
	v_pk_mul_f32 v[54:55], v[52:53], v[0:1] op_sel_hi:[1,0]
	v_pk_mul_f32 v[56:57], v[50:51], v[0:1] op_sel_hi:[1,0]
	ds_read_b128 v[50:53], v15 offset:12288
	ds_read_b128 v[86:89], v15 offset:13312
	ds_read_b128 v[90:93], v15 offset:16384
	ds_read_b128 v[94:97], v15 offset:17408
	v_sub_f32_e32 v47, v47, v63
	v_sub_f32_e32 v46, v46, v63
	v_sub_f32_e32 v49, v49, v63
	s_waitcnt lgkmcnt(0)
	v_pk_fma_f32 v[66:67], v[50:51], v[54:55], v[90:91]
	v_pk_add_f32 v[54:55], v[58:59], v[60:61]
	v_pk_fma_f32 v[68:69], v[52:53], v[56:57], v[92:93]
	s_nop 1
	v_mov_b32_dpp v57, v55 quad_perm:[2,3,0,1] row_mask:0xf bank_mask:0xf
	s_nop 1
	v_mov_b32_dpp v56, v54 quad_perm:[2,3,0,1] row_mask:0xf bank_mask:0xf
	v_sub_f32_e32 v48, v48, v63
	v_pk_mul_f32 v[46:47], v[46:47], v[0:1] op_sel_hi:[1,0]
	v_pk_mul_f32 v[48:49], v[48:49], v[0:1] op_sel_hi:[1,0]
	s_waitcnt lgkmcnt(0)
	v_pk_fma_f32 v[58:59], v[86:87], v[46:47], v[94:95]
	s_waitcnt lgkmcnt(0)
	v_pk_add_f32 v[54:55], v[54:55], v[56:57]
	s_nop 1
	v_mov_b32_dpp v57, v55 row_half_mirror row_mask:0xf bank_mask:0xf
	s_nop 1
	v_mov_b32_dpp v56, v54 row_half_mirror row_mask:0xf bank_mask:0xf
	v_pk_fma_f32 v[60:61], v[88:89], v[48:49], v[96:97]
	v_sub_f32_e32 v45, v45, v63
	v_sub_f32_e32 v44, v44, v63
	v_sub_f32_e32 v43, v43, v63
	s_waitcnt lgkmcnt(0)
	v_pk_add_f32 v[46:47], v[54:55], v[56:57]
	s_nop 1
	v_mov_b32_dpp v49, v47 row_mirror row_mask:0xf bank_mask:0xf
	s_nop 1
	v_mov_b32_dpp v48, v46 row_mirror row_mask:0xf bank_mask:0xf
	v_sub_f32_e32 v42, v42, v63
	v_pk_mul_f32 v[54:55], v[42:43], v[0:1] op_sel_hi:[1,0]
	v_pk_mul_f32 v[56:57], v[44:45], v[0:1] op_sel_hi:[1,0]
	ds_read_b128 v[42:45], v15 offset:14336
	ds_read_b128 v[98:101], v15 offset:15360
	ds_read_b128 v[128:131], v15 offset:18432
	ds_read_b128 v[140:143], v15 offset:19456
	s_waitcnt lgkmcnt(0)
	v_pk_add_f32 v[46:47], v[46:47], v[48:49]
	v_mov_b32_e32 v48, v46
	v_mov_b32_e32 v49, v47
	v_mov_b32_e32 v134, v46
	v_mov_b32_e32 v135, v47
	s_nop 1
	v_permlane16_swap_b32_e32 v48, v134
	v_permlane16_swap_b32_e32 v49, v135
	v_sub_f32_e32 v41, v41, v63
	v_sub_f32_e32 v40, v40, v63
	v_sub_f32_e32 v39, v39, v63
	v_sub_f32_e32 v38, v38, v63
	s_waitcnt lgkmcnt(0)
	v_pk_add_f32 v[46:47], v[48:49], v[134:135]
	v_mov_b32_e32 v48, v46
	v_mov_b32_e32 v49, v47
	v_mov_b32_e32 v134, v46
	v_mov_b32_e32 v135, v47
	s_nop 1
	v_permlane32_swap_b32_e32 v48, v134
	v_permlane32_swap_b32_e32 v49, v135
	v_pk_mul_f32 v[38:39], v[38:39], v[0:1] op_sel_hi:[1,0]
	v_pk_mul_f32 v[40:41], v[40:41], v[0:1] op_sel_hi:[1,0]
	v_pk_fma_f32 v[62:63], v[98:99], v[38:39], v[140:141]
	v_pk_fma_f32 v[64:65], v[100:101], v[40:41], v[142:143]
	s_waitcnt lgkmcnt(0)
; #define LAS __attribute__((address_space(3)))
; __device__ __forceinline__ void row_pass(const Params& P, int l, int mode, LAS float* pl) {
;     ...
;             wave_sum2(s[0], s[1]); wave_sum2(q[0], q[1]);
; #pragma unroll
;             for (int r = 0; r < 2; ++r) { const float mean = s[r] * (1.f / DM); const float var = fmaxf(q[r] * (1.f / DM) - mean * mean, 0.f); const float rstd = 1.f / sqrtf(var + LN_EPS);
; #pragma unroll
;                 for (int j = 0; j < 4; ++j) { const f32x4 g = *(const LAS f32x4*)(pl + 3072 + 4 * lane + 256 * j), bb = *(const LAS f32x4*)(pl + 4096 + 4 * lane + 256 * j); v[r][j] = (v[r][j] - mean) * rstd * g + bb; } }
;         }
;         if (mode != 0) {
; #pragma unroll
;         for (int r = 0; r < 2; ++r) if (ok[r]) {
; #pragma unroll
;             for (int j = 0; j < 4; ++j) __builtin_nontemporal_store(v[r][j], (f32x4*)(dst[r] + 4 * lane + 256 * j)); } }
;         if (make_h) {
;             float s[2], q[2];
; #pragma unroll
;             for (int r = 0; r < 2; ++r) { s[r] = 0.f; q[r] = 0.f;
; #pragma unroll
;                 for (int j = 0; j < 4; ++j) { s[r] += (v[r][j][0] + v[r][j][1]) + (v[r][j][2] + v[r][j][3]); const f32x4 sq = v[r][j] * v[r][j]; q[r] += (sq[0] + sq[1]) + (sq[2] + sq[3]); } }
	v_pk_add_f32 v[46:47], v[48:49], v[134:135]
	v_pk_fma_f32 v[56:57], v[44:45], v[56:57], v[130:131]
	v_pk_mul_f32 v[132:133], v[46:47], s[16:17] op_sel_hi:[1,0]
	v_pk_fma_f32 v[54:55], v[42:43], v[54:55], v[128:129]
	v_fma_f32 v46, -v133, v133, v132
	v_max_f32_e32 v46, 0, v46
	v_add_f32_e32 v46, 0x358637bd, v46
	v_mul_f32_e32 v47, 0x4f800000, v46
	v_cmp_gt_f32_e32 vcc, s17, v46
	v_sub_f32_e32 v41, v73, v133
	v_sub_f32_e32 v40, v72, v133
	v_cndmask_b32_e32 v46, v46, v47, vcc
	v_sqrt_f32_e32 v47, v46
	s_mov_b32 s18, 0x3a800000
	s_mov_b32 s16, 0xf800000
	v_add_u32_e32 v48, -1, v47
	v_fma_f32 v49, -v48, v47, v46
	v_cmp_ge_f32_e64 s[0:1], 0, v49
	v_add_u32_e32 v49, 1, v47
	s_nop 0
	v_cndmask_b32_e64 v48, v47, v48, s[0:1]
	v_fma_f32 v47, -v49, v47, v46
	v_cmp_lt_f32_e64 s[0:1], 0, v47
	s_nop 1
	v_cndmask_b32_e64 v47, v48, v49, s[0:1]
	v_mul_f32_e32 v48, 0x37800000, v47
	v_cndmask_b32_e32 v47, v47, v48, vcc
	v_cmp_class_f32_e32 vcc, v46, v217
	s_nop 1
	v_cndmask_b32_e32 v46, v47, v46, vcc
	v_div_scale_f32 v47, s[0:1], v46, v46, 1.0
	v_rcp_f32_e32 v48, v47
	s_nop 0
	v_fma_f32 v0, -v47, v48, 1.0
	v_fmac_f32_e32 v48, v0, v48
	v_div_scale_f32 v0, vcc, 1.0, v46, 1.0
	v_mul_f32_e32 v38, v0, v48
	v_fma_f32 v39, -v47, v38, v0
	v_fmac_f32_e32 v38, v39, v48
	v_fma_f32 v0, -v47, v38, v0
	v_div_fmas_f32 v0, v0, v48, v38
	v_div_fixup_f32 v0, v0, v46, 1.0
	v_sub_f32_e32 v39, v71, v133
	v_sub_f32_e32 v38, v70, v133
	v_pk_mul_f32 v[40:41], v[40:41], v[0:1] op_sel_hi:[1,0]
	v_pk_mul_f32 v[38:39], v[38:39], v[0:1] op_sel_hi:[1,0]
	v_pk_fma_f32 v[50:51], v[50:51], v[40:41], v[90:91]
	v_pk_fma_f32 v[52:53], v[52:53], v[38:39], v[92:93]
	v_sub_f32_e32 v39, v79, v133
	v_sub_f32_e32 v38, v78, v133
	v_sub_f32_e32 v41, v75, v133
	v_sub_f32_e32 v40, v74, v133
	v_pk_mul_f32 v[40:41], v[40:41], v[0:1] op_sel_hi:[1,0]
	v_pk_mul_f32 v[38:39], v[38:39], v[0:1] op_sel_hi:[1,0]
	v_pk_fma_f32 v[46:47], v[86:87], v[40:41], v[94:95]
	v_pk_fma_f32 v[48:49], v[88:89], v[38:39], v[96:97]
	v_sub_f32_e32 v39, v81, v133
	v_sub_f32_e32 v38, v80, v133
	v_sub_f32_e32 v41, v77, v133
	v_sub_f32_e32 v40, v76, v133
	v_pk_mul_f32 v[40:41], v[40:41], v[0:1] op_sel_hi:[1,0]
	v_pk_mul_f32 v[38:39], v[38:39], v[0:1] op_sel_hi:[1,0]
	v_pk_fma_f32 v[42:43], v[42:43], v[40:41], v[128:129]
	v_pk_fma_f32 v[44:45], v[44:45], v[38:39], v[130:131]
	v_sub_f32_e32 v39, v85, v133
	v_sub_f32_e32 v38, v84, v133
	v_sub_f32_e32 v41, v83, v133
	v_sub_f32_e32 v40, v82, v133
	v_pk_mul_f32 v[70:71], v[40:41], v[0:1] op_sel_hi:[1,0]
	v_pk_mul_f32 v[38:39], v[38:39], v[0:1] op_sel_hi:[1,0]
	v_cndmask_b32_e64 v0, 0, 1, s[12:13]
	v_pk_fma_f32 v[40:41], v[100:101], v[38:39], v[142:143]
	v_pk_fma_f32 v[38:39], v[98:99], v[70:71], v[140:141]
	v_lshl_add_u64 v[70:71], v[108:109], 0, s[4:5]
	v_cmp_ne_u32_e64 s[4:5], 1, v0
	s_andn2_b64 vcc, exec, s[12:13]
	global_store_dwordx4 v[70:71], v[66:69], off nt
	global_store_dwordx4 v[70:71], v[58:61], off offset:1024 nt
	global_store_dwordx4 v[70:71], v[54:57], off offset:2048 nt
	global_store_dwordx4 v[70:71], v[62:65], off offset:3072 nt
	s_cbranch_vccnz .LBB0_1044
	s_lshl_b64 s[0:1], s[10:11], 12
	v_lshl_add_u64 v[70:71], v[108:109], 0, s[0:1]
	global_store_dwordx4 v[70:71], v[50:53], off nt
	global_store_dwordx4 v[70:71], v[46:49], off offset:1024 nt
	global_store_dwordx4 v[70:71], v[42:45], off offset:2048 nt
	global_store_dwordx4 v[70:71], v[38:41], off offset:3072 nt
.LBB0_1044:
	v_pk_mul_f32 v[96:97], v[50:51], v[50:51]
	v_pk_mul_f32 v[94:95], v[52:53], v[52:53]
	v_pk_mul_f32 v[100:101], v[46:47], v[46:47]
	v_mov_b32_e32 v140, v96
	v_mov_b32_e32 v141, v46
	v_mov_b32_e32 v96, v97
	v_mov_b32_e32 v97, v47
	v_add_f32_e32 v91, v50, v51
	v_add_f32_e32 v93, v52, v53
	v_pk_mul_f32 v[98:99], v[48:49], v[48:49]
	v_pk_add_f32 v[96:97], v[140:141], v[96:97]
	v_mov_b32_e32 v140, v94
	v_mov_b32_e32 v141, v48
	v_mov_b32_e32 v94, v95
	v_mov_b32_e32 v95, v49
	v_mov_b32_e32 v90, v100
	v_mov_b32_e32 v92, v101
	v_add_f32_e32 v0, v98, v99
	v_pk_add_f32 v[94:95], v[140:141], v[94:95]
	v_pk_add_f32 v[90:91], v[90:91], v[92:93]
	v_pk_mul_f32 v[128:129], v[42:43], v[42:43]
	v_pk_add_f32 v[94:95], v[96:97], v[94:95]
	v_pk_add_f32 v[90:91], v[90:91], v[0:1]
	v_pk_mul_f32 v[98:99], v[44:45], v[44:45]
	v_pk_add_f32 v[90:91], v[94:95], v[90:91]
	v_mov_b32_e32 v92, v128
	v_mov_b32_e32 v93, v42
	v_mov_b32_e32 v94, v129
	v_mov_b32_e32 v95, v43
	v_pk_add_f32 v[92:93], v[92:93], v[94:95]
	v_mov_b32_e32 v94, v98
	v_mov_b32_e32 v95, v44
	v_mov_b32_e32 v96, v99
	v_mov_b32_e32 v97, v45
	v_pk_mul_f32 v[76:77], v[66:67], v[66:67]
	v_pk_add_f32 v[94:95], v[94:95], v[96:97]
	v_pk_mul_f32 v[74:75], v[68:69], v[68:69]
	v_pk_mul_f32 v[80:81], v[58:59], v[58:59]
	v_pk_add_f32 v[92:93], v[92:93], v[94:95]
	v_mov_b32_e32 v94, v76
	v_mov_b32_e32 v95, v58
	v_mov_b32_e32 v76, v77
	v_mov_b32_e32 v77, v59
	v_add_f32_e32 v71, v66, v67
	v_add_f32_e32 v73, v68, v69
	v_pk_mul_f32 v[78:79], v[60:61], v[60:61]
	v_pk_add_f32 v[76:77], v[94:95], v[76:77]
	v_mov_b32_e32 v94, v74
	v_mov_b32_e32 v95, v60
	v_mov_b32_e32 v74, v75
	v_mov_b32_e32 v75, v61
	v_mov_b32_e32 v70, v80
	v_mov_b32_e32 v72, v81
	v_add_f32_e32 v78, v78, v79
	v_pk_add_f32 v[74:75], v[94:95], v[74:75]
	v_pk_add_f32 v[70:71], v[70:71], v[72:73]
	v_mov_b32_e32 v79, v1
	v_pk_mul_f32 v[84:85], v[54:55], v[54:55]
	v_pk_add_f32 v[74:75], v[76:77], v[74:75]
	v_pk_add_f32 v[70:71], v[70:71], v[78:79]
	v_pk_mul_f32 v[82:83], v[56:57], v[56:57]
	v_pk_add_f32 v[70:71], v[74:75], v[70:71]
	v_mov_b32_e32 v72, v84
	v_mov_b32_e32 v73, v54
	v_mov_b32_e32 v74, v85
	v_mov_b32_e32 v75, v55
	v_pk_add_f32 v[72:73], v[72:73], v[74:75]
	v_mov_b32_e32 v74, v82
	v_mov_b32_e32 v75, v56
	v_mov_b32_e32 v76, v83
	v_mov_b32_e32 v77, v57
	v_pk_add_f32 v[74:75], v[74:75], v[76:77]
	v_pk_mul_f32 v[88:89], v[62:63], v[62:63]
	v_pk_add_f32 v[72:73], v[72:73], v[74:75]
	v_pk_mul_f32 v[86:87], v[64:65], v[64:65]
	v_pk_add_f32 v[70:71], v[72:73], v[70:71]
	v_mov_b32_e32 v72, v88
	v_mov_b32_e32 v73, v62
	v_mov_b32_e32 v74, v89
	v_mov_b32_e32 v75, v63
	v_pk_add_f32 v[72:73], v[72:73], v[74:75]
	v_mov_b32_e32 v74, v86
	v_mov_b32_e32 v75, v64
	v_mov_b32_e32 v76, v87
	v_mov_b32_e32 v77, v65
	v_pk_add_f32 v[74:75], v[74:75], v[76:77]
	v_pk_mul_f32 v[130:131], v[40:41], v[40:41]
	v_pk_add_f32 v[72:73], v[72:73], v[74:75]
	v_pk_mul_f32 v[132:133], v[38:39], v[38:39]
	v_pk_add_f32 v[70:71], v[72:73], v[70:71]
	s_nop 1
	v_mov_b32_dpp v73, v71 quad_perm:[1,0,3,2] row_mask:0xf bank_mask:0xf
	s_nop 1
	v_mov_b32_dpp v72, v70 quad_perm:[1,0,3,2] row_mask:0xf bank_mask:0xf
	v_pk_add_f32 v[90:91], v[92:93], v[90:91]
	v_mov_b32_e32 v92, v132
	v_mov_b32_e32 v93, v38
	v_mov_b32_e32 v74, v133
	s_waitcnt lgkmcnt(0)
; #define LAS __attribute__((address_space(3)))
; __device__ __forceinline__ unsigned cvt_pk_bf16(float lo, float hi) { unsigned r; asm volatile("v_cvt_pk_bf16_f32 %0, %1, %2" : "=v"(r) : "v"(lo), "v"(hi)); return r; }
; __device__ __forceinline__ void row_pass(const Params& P, int l, int mode, LAS float* pl) {
;     ...
;         if (make_h) {
;             float s[2], q[2];
; #pragma unroll
;             for (int r = 0; r < 2; ++r) { s[r] = 0.f; q[r] = 0.f;
; #pragma unroll
;                 for (int j = 0; j < 4; ++j) { s[r] += (v[r][j][0] + v[r][j][1]) + (v[r][j][2] + v[r][j][3]); const f32x4 sq = v[r][j] * v[r][j]; q[r] += (sq[0] + sq[1]) + (sq[2] + sq[3]); } }
;             wave_sum2(s[0], s[1]); wave_sum2(q[0], q[1]);
; #pragma unroll
;             for (int r = 0; r < 2; ++r) if (ok[r]) { const float mean = s[r] * (1.f / DM); const float var = fmaxf(q[r] * (1.f / DM) - mean * mean, 0.f); const float rstd = 1.f / sqrtf(var + LN_EPS);
;                 const LAS float* mm = pl + 5120 + mv[r] * DM;
; #pragma unroll
;                 for (int j = 0; j < 4; ++j) { const f32x4 sh = *(const LAS f32x4*)(mm + 4 * lane + 256 * j), sc1 = *(const LAS f32x4*)(mm + 3072 + 4 * lane + 256 * j);
;                     const f32x4 hv = (v[r][j] - mean) * rstd * sc1 + sh; u32x2 o; o.x = cvt_pk_bf16(hv[0], hv[1]); o.y = cvt_pk_bf16(hv[2], hv[3]);
;                     *(u32x2*)(H + (size_t)row[r] * DM + 4 * lane + 256 * j) = o; } }
	v_pk_add_f32 v[70:71], v[70:71], v[72:73]
	s_nop 1
	v_mov_b32_dpp v73, v71 quad_perm:[2,3,0,1] row_mask:0xf bank_mask:0xf
	s_nop 1
	v_mov_b32_dpp v72, v70 quad_perm:[2,3,0,1] row_mask:0xf bank_mask:0xf
	v_mov_b32_e32 v75, v39
	v_mov_b32_e32 v76, v130
	v_mov_b32_e32 v77, v40
	v_mov_b32_e32 v78, v131
	s_waitcnt lgkmcnt(0)
	v_pk_add_f32 v[70:71], v[70:71], v[72:73]
	s_nop 1
	v_mov_b32_dpp v73, v71 row_half_mirror row_mask:0xf bank_mask:0xf
	s_nop 1
	v_mov_b32_dpp v72, v70 row_half_mirror row_mask:0xf bank_mask:0xf
	v_mov_b32_e32 v79, v41
	v_pk_add_f32 v[74:75], v[92:93], v[74:75]
	v_pk_add_f32 v[76:77], v[76:77], v[78:79]
	s_waitcnt lgkmcnt(0)
	v_pk_add_f32 v[70:71], v[70:71], v[72:73]
	s_nop 1
	v_mov_b32_dpp v73, v71 row_mirror row_mask:0xf bank_mask:0xf
	s_nop 1
	v_mov_b32_dpp v72, v70 row_mirror row_mask:0xf bank_mask:0xf
	v_pk_add_f32 v[74:75], v[74:75], v[76:77]
	s_waitcnt lgkmcnt(0)
	v_pk_add_f32 v[70:71], v[70:71], v[72:73]
	v_pk_add_f32 v[74:75], v[74:75], v[90:91]
	s_nop 1
	v_mov_b32_dpp v77, v75 quad_perm:[1,0,3,2] row_mask:0xf bank_mask:0xf
	s_nop 1
	v_mov_b32_dpp v76, v74 quad_perm:[1,0,3,2] row_mask:0xf bank_mask:0xf
	v_mov_b32_e32 v72, v70
	v_mov_b32_e32 v73, v71
	v_mov_b32_e32 v134, v70
	v_mov_b32_e32 v135, v71
	s_nop 1
	v_permlane16_swap_b32_e32 v72, v134
	v_permlane16_swap_b32_e32 v73, v135
	s_waitcnt lgkmcnt(0)
	v_pk_add_f32 v[74:75], v[74:75], v[76:77]
	s_nop 1
	v_mov_b32_dpp v77, v75 quad_perm:[2,3,0,1] row_mask:0xf bank_mask:0xf
	s_nop 1
	v_mov_b32_dpp v76, v74 quad_perm:[2,3,0,1] row_mask:0xf bank_mask:0xf
	s_waitcnt lgkmcnt(0)
	v_pk_add_f32 v[70:71], v[72:73], v[134:135]
	v_mov_b32_e32 v72, v70
	v_mov_b32_e32 v73, v71
	v_mov_b32_e32 v134, v70
	v_mov_b32_e32 v135, v71
	s_nop 1
	v_permlane32_swap_b32_e32 v72, v134
	v_permlane32_swap_b32_e32 v73, v135
	s_waitcnt lgkmcnt(0)
	v_pk_add_f32 v[74:75], v[74:75], v[76:77]
	s_nop 1
	v_mov_b32_dpp v77, v75 row_half_mirror row_mask:0xf bank_mask:0xf
	s_nop 1
	v_mov_b32_dpp v76, v74 row_half_mirror row_mask:0xf bank_mask:0xf
	s_waitcnt lgkmcnt(0)
	v_pk_add_f32 v[70:71], v[72:73], v[134:135]
	s_waitcnt lgkmcnt(0)
	v_pk_add_f32 v[74:75], v[74:75], v[76:77]
	v_pk_mul_f32 v[82:83], v[70:71], s[18:19] op_sel_hi:[1,0]
	s_nop 1
	v_mov_b32_dpp v77, v75 row_mirror row_mask:0xf bank_mask:0xf
	v_fma_f32 v0, -v83, v83, v82
	v_max_f32_e32 v0, 0, v0
	v_add_f32_e32 v0, 0x358637bd, v0
	v_mul_f32_e32 v70, 0x4f800000, v0
	v_cmp_gt_f32_e32 vcc, s16, v0
	s_nop 1
	v_mov_b32_dpp v76, v74 row_mirror row_mask:0xf bank_mask:0xf
	v_sub_f32_e32 v67, v67, v83
	v_cndmask_b32_e32 v0, v0, v70, vcc
	v_sqrt_f32_e32 v78, v0
	v_sub_f32_e32 v66, v66, v83
	s_waitcnt lgkmcnt(0)
	v_pk_add_f32 v[70:71], v[74:75], v[76:77]
	v_sub_f32_e32 v69, v69, v83
	v_add_u32_e32 v74, -1, v78
	v_fma_f32 v75, -v74, v78, v0
	v_cmp_ge_f32_e64 s[0:1], 0, v75
	v_add_u32_e32 v75, 1, v78
	v_fma_f32 v76, -v75, v78, v0
	v_cndmask_b32_e64 v74, v78, v74, s[0:1]
	v_cmp_lt_f32_e64 s[0:1], 0, v76
	v_sub_f32_e32 v68, v68, v83
	v_sub_f32_e32 v59, v59, v83
	v_cndmask_b32_e64 v74, v74, v75, s[0:1]
	v_mul_f32_e32 v75, 0x37800000, v74
	v_cndmask_b32_e32 v74, v74, v75, vcc
	v_cmp_class_f32_e32 vcc, v0, v217
	v_sub_f32_e32 v58, v58, v83
	v_sub_f32_e32 v61, v61, v83
	v_cndmask_b32_e32 v0, v74, v0, vcc
	v_div_scale_f32 v74, s[0:1], v0, v0, 1.0
	v_rcp_f32_e32 v75, v74
	s_lshl_b64 s[0:1], s[14:15], 11
	v_sub_f32_e32 v60, v60, v83
	v_fma_f32 v76, -v74, v75, 1.0
	v_fmac_f32_e32 v75, v76, v75
	v_div_scale_f32 v76, vcc, 1.0, v0, 1.0
	v_mul_f32_e32 v77, v76, v75
	v_fma_f32 v78, -v74, v77, v76
	v_fmac_f32_e32 v77, v78, v75
	v_fma_f32 v74, -v74, v77, v76
	v_div_fmas_f32 v74, v74, v75, v77
	v_div_fixup_f32 v0, v74, v0, 1.0
	ds_read_b128 v[74:77], v127 offset:20480
	ds_read_b128 v[78:81], v127 offset:32768
	v_pk_mul_f32 v[66:67], v[66:67], v[0:1] op_sel_hi:[1,0]
	v_pk_mul_f32 v[68:69], v[68:69], v[0:1] op_sel_hi:[1,0]
	v_pk_mul_f32 v[58:59], v[58:59], v[0:1] op_sel_hi:[1,0]
	v_pk_mul_f32 v[60:61], v[60:61], v[0:1] op_sel_hi:[1,0]
	s_waitcnt lgkmcnt(0)
	v_pk_fma_f32 v[66:67], v[78:79], v[66:67], v[74:75]
	v_lshl_add_u64 v[78:79], v[106:107], 0, s[0:1]
	v_pk_fma_f32 v[68:69], v[80:81], v[68:69], v[76:77]
	v_cvt_pk_bf16_f32 v66, v66, v67
	v_mov_b32_e32 v72, v70
	v_mov_b32_e32 v73, v71
	v_mov_b32_e32 v134, v70
	v_mov_b32_e32 v135, v71
	s_nop 1
	v_permlane16_swap_b32_e32 v72, v134
	v_permlane16_swap_b32_e32 v73, v135
	v_cvt_pk_bf16_f32 v67, v68, v69
	global_store_dwordx2 v[78:79], v[66:67], off
	ds_read_b128 v[66:69], v127 offset:21504
	ds_read_b128 v[74:77], v127 offset:33792
	v_sub_f32_e32 v55, v55, v83
	v_sub_f32_e32 v54, v54, v83
	v_sub_f32_e32 v57, v57, v83
	v_sub_f32_e32 v56, v56, v83
	s_waitcnt lgkmcnt(0)
	v_pk_fma_f32 v[58:59], v[74:75], v[58:59], v[66:67]
	v_pk_fma_f32 v[60:61], v[76:77], v[60:61], v[68:69]
	v_cvt_pk_bf16_f32 v58, v58, v59
	v_pk_mul_f32 v[54:55], v[54:55], v[0:1] op_sel_hi:[1,0]
	v_cvt_pk_bf16_f32 v59, v60, v61
	global_store_dwordx2 v[78:79], v[58:59], off offset:512
	ds_read_b128 v[58:61], v127 offset:22528
	ds_read_b128 v[66:69], v127 offset:34816
	v_pk_mul_f32 v[56:57], v[56:57], v[0:1] op_sel_hi:[1,0]
	v_pk_add_f32 v[70:71], v[72:73], v[134:135]
	v_mov_b32_e32 v72, v70
	v_mov_b32_e32 v73, v71
	v_mov_b32_e32 v134, v70
	v_mov_b32_e32 v135, v71
	s_nop 1
	v_permlane32_swap_b32_e32 v72, v134
	v_permlane32_swap_b32_e32 v73, v135
	s_waitcnt lgkmcnt(0)
	v_pk_fma_f32 v[54:55], v[54:55], v[66:67], v[58:59]
	v_pk_fma_f32 v[56:57], v[56:57], v[68:69], v[60:61]
	v_cvt_pk_bf16_f32 v54, v54, v55
	v_sub_f32_e32 v63, v63, v83
	v_cvt_pk_bf16_f32 v55, v56, v57
	global_store_dwordx2 v[78:79], v[54:55], off offset:1024
	ds_read_b128 v[54:57], v127 offset:23552
	ds_read_b128 v[58:61], v127 offset:35840
	v_sub_f32_e32 v62, v62, v83
	v_sub_f32_e32 v65, v65, v83
	v_sub_f32_e32 v64, v64, v83
	v_pk_mul_f32 v[62:63], v[62:63], v[0:1] op_sel_hi:[1,0]
	v_pk_mul_f32 v[64:65], v[64:65], v[0:1] op_sel_hi:[1,0]
	s_waitcnt lgkmcnt(0)
	v_pk_fma_f32 v[54:55], v[62:63], v[58:59], v[54:55]
	s_and_b64 vcc, exec, s[4:5]
	v_pk_fma_f32 v[56:57], v[64:65], v[60:61], v[56:57]
	v_cvt_pk_bf16_f32 v54, v54, v55
	s_nop 0
	v_cvt_pk_bf16_f32 v55, v56, v57
	global_store_dwordx2 v[78:79], v[54:55], off offset:1536
	s_cbranch_vccnz .LBB0_996
; #define LAS __attribute__((address_space(3)))
; __device__ __forceinline__ unsigned cvt_pk_bf16(float lo, float hi) { unsigned r; asm volatile("v_cvt_pk_bf16_f32 %0, %1, %2" : "=v"(r) : "v"(lo), "v"(hi)); return r; }
; __device__ __forceinline__ void row_pass(const Params& P, int l, int mode, LAS float* pl) {
;     ...
;             for (int r = 0; r < 2; ++r) if (ok[r]) { const float mean = s[r] * (1.f / DM); const float var = fmaxf(q[r] * (1.f / DM) - mean * mean, 0.f); const float rstd = 1.f / sqrtf(var + LN_EPS);
;                 const LAS float* mm = pl + 5120 + mv[r] * DM;
; #pragma unroll
;                 for (int j = 0; j < 4; ++j) { const f32x4 sh = *(const LAS f32x4*)(mm + 4 * lane + 256 * j), sc1 = *(const LAS f32x4*)(mm + 3072 + 4 * lane + 256 * j);
;                     const f32x4 hv = (v[r][j] - mean) * rstd * sc1 + sh; u32x2 o; o.x = cvt_pk_bf16(hv[0], hv[1]); o.y = cvt_pk_bf16(hv[2], hv[3]);
;                     *(u32x2*)(H + (size_t)row[r] * DM + 4 * lane + 256 * j) = o; } }
	v_pk_add_f32 v[54:55], v[72:73], v[134:135]
	s_nop 0
	v_pk_mul_f32 v[62:63], v[54:55], s[18:19] op_sel_hi:[1,0]
	s_nop 0
	v_fma_f32 v0, -v63, v63, v62
	v_max_f32_e32 v0, 0, v0
	v_add_f32_e32 v0, 0x358637bd, v0
	v_mul_f32_e32 v54, 0x4f800000, v0
	v_cmp_gt_f32_e32 vcc, s16, v0
	v_sub_f32_e32 v51, v51, v63
	v_sub_f32_e32 v50, v50, v63
	v_cndmask_b32_e32 v0, v0, v54, vcc
	v_sqrt_f32_e32 v54, v0
	v_sub_f32_e32 v53, v53, v63
	v_sub_f32_e32 v52, v52, v63
	v_sub_f32_e32 v47, v47, v63
	v_add_u32_e32 v55, -1, v54
	v_fma_f32 v57, -v55, v54, v0
	v_add_u32_e32 v56, 1, v54
	v_cmp_ge_f32_e64 s[0:1], 0, v57
	v_sub_f32_e32 v46, v46, v63
	v_sub_f32_e32 v49, v49, v63
	v_cndmask_b32_e64 v55, v54, v55, s[0:1]
	v_fma_f32 v54, -v56, v54, v0
	v_cmp_lt_f32_e64 s[0:1], 0, v54
	v_sub_f32_e32 v48, v48, v63
	v_sub_f32_e32 v43, v43, v63
	v_cndmask_b32_e64 v54, v55, v56, s[0:1]
	v_mul_f32_e32 v55, 0x37800000, v54
	v_cndmask_b32_e32 v54, v54, v55, vcc
	v_cmp_class_f32_e32 vcc, v0, v217
	v_sub_f32_e32 v42, v42, v63
	v_sub_f32_e32 v45, v45, v63
	v_cndmask_b32_e32 v0, v54, v0, vcc
	v_div_scale_f32 v54, s[0:1], v0, v0, 1.0
	v_rcp_f32_e32 v55, v54
	s_lshl_b64 s[0:1], s[10:11], 11
	v_sub_f32_e32 v44, v44, v63
	v_sub_f32_e32 v39, v39, v63
	v_fma_f32 v56, -v54, v55, 1.0
	v_fmac_f32_e32 v55, v56, v55
	v_div_scale_f32 v56, vcc, 1.0, v0, 1.0
	v_mul_f32_e32 v57, v56, v55
	v_fma_f32 v58, -v54, v57, v56
	v_fmac_f32_e32 v57, v58, v55
	v_fma_f32 v54, -v54, v57, v56
	v_div_fmas_f32 v54, v54, v55, v57
	v_div_fixup_f32 v0, v54, v0, 1.0
	ds_read_b128 v[54:57], v126 offset:20480
	ds_read_b128 v[58:61], v126 offset:32768
	v_pk_mul_f32 v[50:51], v[50:51], v[0:1] op_sel_hi:[1,0]
	v_pk_mul_f32 v[52:53], v[52:53], v[0:1] op_sel_hi:[1,0]
	v_pk_mul_f32 v[46:47], v[46:47], v[0:1] op_sel_hi:[1,0]
	v_pk_mul_f32 v[48:49], v[48:49], v[0:1] op_sel_hi:[1,0]
	s_waitcnt lgkmcnt(0)
	v_pk_fma_f32 v[50:51], v[50:51], v[58:59], v[54:55]
	v_lshl_add_u64 v[58:59], v[106:107], 0, s[0:1]
	v_pk_fma_f32 v[52:53], v[52:53], v[60:61], v[56:57]
	v_cvt_pk_bf16_f32 v50, v50, v51
	v_pk_mul_f32 v[42:43], v[42:43], v[0:1] op_sel_hi:[1,0]
	v_cvt_pk_bf16_f32 v51, v52, v53
	global_store_dwordx2 v[58:59], v[50:51], off
	ds_read_b128 v[50:53], v126 offset:21504
	ds_read_b128 v[54:57], v126 offset:33792
	v_pk_mul_f32 v[44:45], v[44:45], v[0:1] op_sel_hi:[1,0]
	v_sub_f32_e32 v38, v38, v63
	v_sub_f32_e32 v41, v41, v63
	v_sub_f32_e32 v40, v40, v63
	s_waitcnt lgkmcnt(0)
	v_pk_fma_f32 v[46:47], v[46:47], v[54:55], v[50:51]
	v_pk_fma_f32 v[48:49], v[48:49], v[56:57], v[52:53]
	v_cvt_pk_bf16_f32 v46, v46, v47
	v_pk_mul_f32 v[38:39], v[38:39], v[0:1] op_sel_hi:[1,0]
	v_cvt_pk_bf16_f32 v47, v48, v49
	global_store_dwordx2 v[58:59], v[46:47], off offset:512
	ds_read_b128 v[46:49], v126 offset:22528
	ds_read_b128 v[50:53], v126 offset:34816
	v_pk_mul_f32 v[40:41], v[40:41], v[0:1] op_sel_hi:[1,0]
	s_waitcnt lgkmcnt(0)
	v_pk_fma_f32 v[42:43], v[42:43], v[50:51], v[46:47]
	v_pk_fma_f32 v[44:45], v[44:45], v[52:53], v[48:49]
	v_cvt_pk_bf16_f32 v42, v42, v43
	s_nop 0
	v_cvt_pk_bf16_f32 v43, v44, v45
	global_store_dwordx2 v[58:59], v[42:43], off offset:1024
	ds_read_b128 v[42:45], v126 offset:23552
	ds_read_b128 v[46:49], v126 offset:35840
	s_waitcnt lgkmcnt(0)
	v_pk_fma_f32 v[38:39], v[38:39], v[46:47], v[42:43]
	v_pk_fma_f32 v[40:41], v[40:41], v[48:49], v[44:45]
	v_cvt_pk_bf16_f32 v38, v38, v39
	s_nop 0
	v_cvt_pk_bf16_f32 v39, v40, v41
	global_store_dwordx2 v[58:59], v[38:39], off offset:1536
	s_branch .LBB0_996

; #define LAS __attribute__((address_space(3)))
; __device__ __forceinline__ void row_pass(const Params& P, int l, int mode, LAS float* pl) {
;     ...
;             dst[r] = (lastl && mode == 2) ? P.out + (size_t)ii * DM : xres + (size_t)row[r] * DM;
;             if (mode != 0) {
;                 if (lat) {
; #pragma unroll
;                     for (int j = 0; j < 4; ++j) { const u32x2 yy = yr[r][j];
;                         yv[r][j][0] = __uint_as_float(yy.x << 16); yv[r][j][1] = __uint_as_float(yy.x & 0xffff0000u); yv[r][j][2] = __uint_as_float(yy.y << 16); yv[r][j][3] = __uint_as_float(yy.y & 0xffff0000u); }
;                 } else {
;                     const int nsl = (mode == 1) ? 3 : 11;
; #pragma unroll
;                     for (int j = 0; j < 4; ++j) { const float* yq = y32 + (size_t)(b * CTXL + (w - SEQ)) * DM + 4 * lane + 256 * j; f32x4 a = *(const f32x4*)yq;
;                         for (int sl = 1; sl < nsl; ++sl) a = a + *(const f32x4*)(yq + (size_t)sl * 512 * DM);
;                         yv[r][j] = a; }
;                 }
;             }
;         }
;         if (mode != 0) {
;             float s[2], q[2];
; #pragma unroll
;             for (int r = 0; r < 2; ++r) { const LAS float* gm = pl + mv[r] * DM; s[r] = 0.f; q[r] = 0.f;
; #pragma unroll
;                 for (int j = 0; j < 4; ++j) { const f32x4 g = *(const LAS f32x4*)(gm + 4 * lane + 256 * j); v[r][j] = v[r][j] * ALPHA + g * yv[r][j];
;                     s[r] += (v[r][j][0] + v[r][j][1]) + (v[r][j][2] + v[r][j][3]); const f32x4 sq = v[r][j] * v[r][j]; q[r] += (sq[0] + sq[1]) + (sq[2] + sq[3]); } }
;             wave_sum2(s[0], s[1]); wave_sum2(q[0], q[1]);
.LBB0_1305:
	s_mul_i32 s18, s26, 0x2100
	s_mul_i32 s19, s21, 0x2100
	s_add_i32 s18, s18, s22
	s_add_i32 s20, s19, s20
	s_and_b64 s[22:23], s[38:39], exec
	s_cselect_b32 s22, s2, s20
	s_ashr_i32 s23, s22, 31
	s_lshl_b64 s[22:23], s[22:23], 12
	s_add_u32 s22, s14, s22
	s_addc_u32 s23, s15, s23
	s_lshl_b32 s2, s21, 12
	s_and_b64 s[0:1], s[0:1], exec
	s_cselect_b32 s0, s2, 0x2000
	v_add_u32_e32 v98, s0, v15
	ds_read_b128 v[100:103], v98
	ds_read_b128 v[104:107], v98 offset:1024
	s_mov_b32 s30, 0x3fd744fd
	s_lshl_b32 s2, s26, 12
	s_and_b64 s[0:1], exec, s[10:11]
	s_waitcnt lgkmcnt(1)
	v_pk_mul_f32 v[72:73], v[102:103], v[72:73]
	v_pk_mul_f32 v[70:71], v[100:101], v[70:71]
	v_pk_fma_f32 v[68:69], v[68:69], s[30:31], v[72:73] op_sel_hi:[1,0,1]
	ds_read_b128 v[100:103], v98 offset:2048
	v_pk_fma_f32 v[66:67], v[66:67], s[30:31], v[70:71] op_sel_hi:[1,0,1]
	v_pk_mul_f32 v[70:71], v[68:69], v[68:69]
	s_waitcnt lgkmcnt(1)
	v_pk_mul_f32 v[72:73], v[106:107], v[76:77]
	v_add_f32_e32 v0, v70, v71
	v_pk_mul_f32 v[70:71], v[104:105], v[74:75]
	v_pk_fma_f32 v[74:75], v[64:65], s[30:31], v[72:73] op_sel_hi:[1,0,1]
	v_pk_fma_f32 v[70:71], v[62:63], s[30:31], v[70:71] op_sel_hi:[1,0,1]
	ds_read_b128 v[62:65], v98 offset:3072
	v_pk_mul_f32 v[106:107], v[70:71], v[70:71]
	v_pk_mul_f32 v[112:113], v[66:67], v[66:67]
	v_pk_mul_f32 v[104:105], v[74:75], v[74:75]
	s_waitcnt lgkmcnt(1)
	v_pk_mul_f32 v[76:77], v[102:103], v[84:85]
	v_pk_mul_f32 v[72:73], v[100:101], v[82:83]
	v_mov_b32_e32 v100, v106
	v_mov_b32_e32 v101, v70
	v_mov_b32_e32 v102, v107
	v_mov_b32_e32 v103, v71
	v_add_f32_e32 v109, v66, v67
	v_add_f32_e32 v111, v68, v69
	v_mov_b32_e32 v108, v112
	v_mov_b32_e32 v110, v113
	v_pk_add_f32 v[100:101], v[100:101], v[102:103]
	v_mov_b32_e32 v102, v104
	v_mov_b32_e32 v103, v74
	v_mov_b32_e32 v104, v105
	v_mov_b32_e32 v105, v75
	v_pk_fma_f32 v[72:73], v[58:59], s[30:31], v[72:73] op_sel_hi:[1,0,1]
	v_pk_add_f32 v[84:85], v[108:109], v[110:111]
	v_pk_add_f32 v[102:103], v[102:103], v[104:105]
	v_pk_fma_f32 v[76:77], v[60:61], s[30:31], v[76:77] op_sel_hi:[1,0,1]
	v_pk_mul_f32 v[60:61], v[72:73], v[72:73]
	v_pk_add_f32 v[84:85], v[84:85], v[0:1]
	v_pk_add_f32 v[100:101], v[100:101], v[102:103]
	v_pk_mul_f32 v[58:59], v[76:77], v[76:77]
	s_waitcnt lgkmcnt(0)
	v_pk_mul_f32 v[62:63], v[62:63], v[78:79]
	v_pk_add_f32 v[84:85], v[84:85], v[100:101]
	v_mov_b32_e32 v100, v60
	v_mov_b32_e32 v101, v72
	v_mov_b32_e32 v60, v61
	v_mov_b32_e32 v61, v73
	v_pk_mul_f32 v[64:65], v[64:65], v[80:81]
	v_pk_fma_f32 v[62:63], v[54:55], s[30:31], v[62:63] op_sel_hi:[1,0,1]
	v_pk_add_f32 v[60:61], v[100:101], v[60:61]
	v_mov_b32_e32 v100, v58
	v_mov_b32_e32 v101, v76
	v_mov_b32_e32 v58, v59
	v_mov_b32_e32 v59, v77
	v_pk_fma_f32 v[64:65], v[56:57], s[30:31], v[64:65] op_sel_hi:[1,0,1]
	v_pk_mul_f32 v[82:83], v[62:63], v[62:63]
	v_pk_add_f32 v[58:59], v[100:101], v[58:59]
	v_pk_mul_f32 v[78:79], v[64:65], v[64:65]
	v_pk_add_f32 v[58:59], v[60:61], v[58:59]
	v_mov_b32_e32 v60, v82
	v_mov_b32_e32 v61, v62
	v_mov_b32_e32 v82, v83
	v_mov_b32_e32 v83, v63
	v_pk_add_f32 v[60:61], v[60:61], v[82:83]
	v_mov_b32_e32 v82, v78
	v_mov_b32_e32 v83, v64
	v_mov_b32_e32 v78, v79
	v_mov_b32_e32 v79, v65
	s_cselect_b32 s0, s2, 0x2000
	v_pk_add_f32 v[78:79], v[82:83], v[78:79]
	v_add_u32_e32 v80, s0, v15
	v_pk_add_f32 v[58:59], v[84:85], v[58:59]
	v_pk_add_f32 v[60:61], v[60:61], v[78:79]
	ds_read_b128 v[54:57], v80
	v_pk_add_f32 v[78:79], v[58:59], v[60:61]
	s_nop 1
	v_mov_b32_dpp v83, v79 quad_perm:[1,0,3,2] row_mask:0xf bank_mask:0xf
	s_nop 1
	v_mov_b32_dpp v82, v78 quad_perm:[1,0,3,2] row_mask:0xf bank_mask:0xf
	ds_read_b128 v[58:61], v80 offset:1024
	s_waitcnt lgkmcnt(0)
	v_pk_mul_f32 v[56:57], v[56:57], v[88:89]
	v_pk_mul_f32 v[54:55], v[54:55], v[86:87]
	v_pk_fma_f32 v[52:53], v[52:53], s[30:31], v[56:57] op_sel_hi:[1,0,1]
	s_waitcnt lgkmcnt(0)
	v_pk_add_f32 v[56:57], v[78:79], v[82:83]
	s_nop 1
	v_mov_b32_dpp v79, v57 quad_perm:[2,3,0,1] row_mask:0xf bank_mask:0xf
	s_nop 1
	v_mov_b32_dpp v78, v56 quad_perm:[2,3,0,1] row_mask:0xf bank_mask:0xf
	v_pk_fma_f32 v[50:51], v[50:51], s[30:31], v[54:55] op_sel_hi:[1,0,1]
	s_mov_b32 s10, 0x3a800000
	s_waitcnt lgkmcnt(0)
	v_pk_mul_f32 v[60:61], v[60:61], v[92:93]
	v_pk_mul_f32 v[58:59], v[58:59], v[90:91]
	s_waitcnt lgkmcnt(0)
	v_pk_add_f32 v[54:55], v[56:57], v[78:79]
	s_nop 1
	v_mov_b32_dpp v57, v55 row_half_mirror row_mask:0xf bank_mask:0xf
	s_nop 1
	v_mov_b32_dpp v56, v54 row_half_mirror row_mask:0xf bank_mask:0xf
	v_pk_mul_f32 v[78:79], v[52:53], v[52:53]
	v_pk_fma_f32 v[46:47], v[46:47], s[30:31], v[58:59] op_sel_hi:[1,0,1]
	v_add_f32_e32 v106, v78, v79
	v_pk_fma_f32 v[48:49], v[48:49], s[30:31], v[60:61] op_sel_hi:[1,0,1]
	s_waitcnt lgkmcnt(0)
	v_pk_add_f32 v[78:79], v[54:55], v[56:57]
	s_nop 1
	v_mov_b32_dpp v83, v79 row_mirror row_mask:0xf bank_mask:0xf
	s_nop 1
	v_mov_b32_dpp v82, v78 row_mirror row_mask:0xf bank_mask:0xf
	ds_read_b128 v[54:57], v80 offset:2048
	ds_read_b128 v[58:61], v80 offset:3072
	v_pk_mul_f32 v[104:105], v[50:51], v[50:51]
	v_add_f32_e32 v101, v50, v51
	s_waitcnt lgkmcnt(0)
	v_pk_add_f32 v[78:79], v[78:79], v[82:83]
	v_mov_b32_e32 v82, v78
	v_mov_b32_e32 v83, v79
	v_mov_b32_e32 v192, v78
	v_mov_b32_e32 v193, v79
	s_nop 1
	v_permlane16_swap_b32_e32 v82, v192
	v_permlane16_swap_b32_e32 v83, v193
	s_waitcnt lgkmcnt(0)
	v_pk_mul_f32 v[58:59], v[58:59], v[138:139]
	v_add_f32_e32 v103, v52, v53
	v_pk_mul_f32 v[110:111], v[46:47], v[46:47]
	v_pk_fma_f32 v[38:39], v[38:39], s[30:31], v[58:59] op_sel_hi:[1,0,1]
	s_waitcnt lgkmcnt(0)
; #define LAS __attribute__((address_space(3)))
; __device__ __forceinline__ void row_pass(const Params& P, int l, int mode, LAS float* pl) {
;     ...
;                 for (int j = 0; j < 4; ++j) { const f32x4 g = *(const LAS f32x4*)(gm + 4 * lane + 256 * j); v[r][j] = v[r][j] * ALPHA + g * yv[r][j];
;                     s[r] += (v[r][j][0] + v[r][j][1]) + (v[r][j][2] + v[r][j][3]); const f32x4 sq = v[r][j] * v[r][j]; q[r] += (sq[0] + sq[1]) + (sq[2] + sq[3]); } }
;             wave_sum2(s[0], s[1]); wave_sum2(q[0], q[1]);
; #pragma unroll
;             for (int r = 0; r < 2; ++r) { const float mean = s[r] * (1.f / DM); const float var = fmaxf(q[r] * (1.f / DM) - mean * mean, 0.f); const float rstd = 1.f / sqrtf(var + LN_EPS);
; #pragma unroll
;                 for (int j = 0; j < 4; ++j) { const f32x4 g = *(const LAS f32x4*)(pl + 3072 + 4 * lane + 256 * j), bb = *(const LAS f32x4*)(pl + 4096 + 4 * lane + 256 * j); v[r][j] = (v[r][j] - mean) * rstd * g + bb; } }
	v_pk_add_f32 v[78:79], v[82:83], v[192:193]
	v_mov_b32_e32 v82, v78
	v_mov_b32_e32 v83, v79
	v_mov_b32_e32 v192, v78
	v_mov_b32_e32 v193, v79
	s_nop 1
	v_permlane32_swap_b32_e32 v82, v192
	v_permlane32_swap_b32_e32 v83, v193
	v_mov_b32_e32 v100, v104
	v_mov_b32_e32 v102, v105
	v_pk_mul_f32 v[108:109], v[48:49], v[48:49]
	v_pk_add_f32 v[100:101], v[100:101], v[102:103]
	s_waitcnt lgkmcnt(0)
	v_pk_add_f32 v[78:79], v[82:83], v[192:193]
	v_mov_b32_e32 v107, v1
	v_pk_mul_f32 v[78:79], v[78:79], s[10:11] op_sel_hi:[1,0]
	v_mov_b32_e32 v102, v110
	v_fma_f32 v0, -v79, v79, v78
	v_max_f32_e32 v0, 0, v0
	v_add_f32_e32 v0, 0x358637bd, v0
	v_mul_f32_e32 v78, 0x4f800000, v0
	v_cmp_gt_f32_e32 vcc, s69, v0
	v_mov_b32_e32 v103, v46
	v_mov_b32_e32 v104, v111
	v_cndmask_b32_e32 v0, v0, v78, vcc
	v_sqrt_f32_e32 v78, v0
	v_mov_b32_e32 v105, v47
	v_pk_mul_f32 v[54:55], v[54:55], v[94:95]
	v_pk_add_f32 v[100:101], v[100:101], v[106:107]
	v_add_u32_e32 v58, -1, v78
	v_fma_f32 v59, -v58, v78, v0
	v_cmp_ge_f32_e64 s[0:1], 0, v59
	v_add_u32_e32 v59, 1, v78
	v_pk_add_f32 v[102:103], v[102:103], v[104:105]
	v_mov_b32_e32 v104, v108
	v_mov_b32_e32 v105, v48
	v_mov_b32_e32 v106, v109
	v_mov_b32_e32 v107, v49
	v_pk_mul_f32 v[56:57], v[56:57], v[96:97]
	v_pk_fma_f32 v[42:43], v[42:43], s[30:31], v[54:55] op_sel_hi:[1,0,1]
	v_cndmask_b32_e64 v58, v78, v58, s[0:1]
	v_fma_f32 v78, -v59, v78, v0
	v_pk_add_f32 v[104:105], v[104:105], v[106:107]
	v_pk_fma_f32 v[44:45], v[44:45], s[30:31], v[56:57] op_sel_hi:[1,0,1]
	v_pk_mul_f32 v[56:57], v[42:43], v[42:43]
	v_cmp_lt_f32_e64 s[0:1], 0, v78
	v_pk_add_f32 v[102:103], v[102:103], v[104:105]
	v_pk_mul_f32 v[54:55], v[44:45], v[44:45]
	v_cndmask_b32_e64 v58, v58, v59, s[0:1]
	v_pk_add_f32 v[100:101], v[100:101], v[102:103]
	v_mov_b32_e32 v102, v56
	v_mov_b32_e32 v103, v42
	v_mov_b32_e32 v56, v57
	v_mov_b32_e32 v57, v43
	v_pk_mul_f32 v[60:61], v[60:61], v[140:141]
	v_mul_f32_e32 v59, 0x37800000, v58
	v_pk_add_f32 v[56:57], v[102:103], v[56:57]
	v_mov_b32_e32 v102, v54
	v_mov_b32_e32 v103, v44
	v_mov_b32_e32 v54, v55
	v_mov_b32_e32 v55, v45
	v_cndmask_b32_e32 v58, v58, v59, vcc
	v_cmp_class_f32_e32 vcc, v0, v217
	v_pk_fma_f32 v[40:41], v[40:41], s[30:31], v[60:61] op_sel_hi:[1,0,1]
	v_pk_mul_f32 v[60:61], v[38:39], v[38:39]
	v_pk_add_f32 v[54:55], v[102:103], v[54:55]
	v_cndmask_b32_e32 v0, v58, v0, vcc
	v_pk_mul_f32 v[58:59], v[40:41], v[40:41]
	v_pk_add_f32 v[54:55], v[56:57], v[54:55]
	v_mov_b32_e32 v56, v60
	v_mov_b32_e32 v57, v38
	v_mov_b32_e32 v60, v61
	v_mov_b32_e32 v61, v39
	v_pk_add_f32 v[56:57], v[56:57], v[60:61]
	v_mov_b32_e32 v60, v58
	v_mov_b32_e32 v61, v40
	v_mov_b32_e32 v58, v59
	v_mov_b32_e32 v59, v41
	v_pk_add_f32 v[58:59], v[60:61], v[58:59]
	v_pk_add_f32 v[54:55], v[100:101], v[54:55]
	v_pk_add_f32 v[56:57], v[56:57], v[58:59]
	v_div_scale_f32 v78, s[0:1], v0, v0, 1.0
	v_pk_add_f32 v[54:55], v[54:55], v[56:57]
	s_nop 1
	v_mov_b32_dpp v57, v55 quad_perm:[1,0,3,2] row_mask:0xf bank_mask:0xf
	s_nop 1
	v_mov_b32_dpp v56, v54 quad_perm:[1,0,3,2] row_mask:0xf bank_mask:0xf
	v_rcp_f32_e32 v81, v78
	v_sub_f32_e32 v59, v75, v79
	v_sub_f32_e32 v58, v74, v79
	v_sub_f32_e32 v61, v71, v79
	s_waitcnt lgkmcnt(0)
	v_pk_add_f32 v[54:55], v[54:55], v[56:57]
	s_nop 1
	v_mov_b32_dpp v57, v55 quad_perm:[2,3,0,1] row_mask:0xf bank_mask:0xf
	s_nop 1
	v_mov_b32_dpp v56, v54 quad_perm:[2,3,0,1] row_mask:0xf bank_mask:0xf
	v_fma_f32 v82, -v78, v81, 1.0
	v_fmac_f32_e32 v81, v82, v81
	v_div_scale_f32 v82, vcc, 1.0, v0, 1.0
	s_waitcnt lgkmcnt(0)
	v_pk_add_f32 v[54:55], v[54:55], v[56:57]
	s_nop 1
	v_mov_b32_dpp v57, v55 row_half_mirror row_mask:0xf bank_mask:0xf
	s_nop 1
	v_mov_b32_dpp v56, v54 row_half_mirror row_mask:0xf bank_mask:0xf
	v_mul_f32_e32 v83, v82, v81
	v_fma_f32 v84, -v78, v83, v82
	v_fmac_f32_e32 v83, v84, v81
	v_fma_f32 v78, -v78, v83, v82
	s_waitcnt lgkmcnt(0)
	v_pk_add_f32 v[54:55], v[54:55], v[56:57]
	s_nop 1
	v_mov_b32_dpp v57, v55 row_mirror row_mask:0xf bank_mask:0xf
	s_nop 1
	v_mov_b32_dpp v56, v54 row_mirror row_mask:0xf bank_mask:0xf
	v_div_fmas_f32 v78, v78, v81, v83
	ds_read_b128 v[82:85], v15 offset:12288
	ds_read_b128 v[86:89], v15 offset:13312
	ds_read_b128 v[90:93], v15 offset:16384
	ds_read_b128 v[94:97], v15 offset:17408
	v_div_fixup_f32 v0, v78, v0, 1.0
	v_sub_f32_e32 v60, v70, v79
	s_waitcnt lgkmcnt(0)
	v_pk_add_f32 v[54:55], v[54:55], v[56:57]
	v_mov_b32_e32 v56, v54
	v_mov_b32_e32 v57, v55
	v_mov_b32_e32 v192, v54
	v_mov_b32_e32 v193, v55
	s_nop 1
	v_permlane16_swap_b32_e32 v56, v192
	v_permlane16_swap_b32_e32 v57, v193
	v_pk_mul_f32 v[70:71], v[60:61], v[0:1] op_sel_hi:[1,0]
	v_pk_mul_f32 v[58:59], v[58:59], v[0:1] op_sel_hi:[1,0]
	v_sub_f32_e32 v73, v73, v79
	s_waitcnt lgkmcnt(0)
	v_pk_fma_f32 v[60:61], v[88:89], v[58:59], v[96:97]
	s_waitcnt lgkmcnt(0)
	v_pk_add_f32 v[112:113], v[56:57], v[192:193]
	v_pk_fma_f32 v[58:59], v[86:87], v[70:71], v[94:95]
	v_sub_f32_e32 v71, v77, v79
	v_sub_f32_e32 v70, v76, v79
	v_sub_f32_e32 v72, v72, v79
	v_mov_b32_e32 v114, v112
	v_mov_b32_e32 v115, v113
	v_mov_b32_e32 v192, v112
	v_mov_b32_e32 v193, v113
	s_nop 1
	v_permlane32_swap_b32_e32 v114, v192
	v_permlane32_swap_b32_e32 v115, v193
	v_pk_mul_f32 v[108:109], v[72:73], v[0:1] op_sel_hi:[1,0]
	v_pk_mul_f32 v[110:111], v[70:71], v[0:1] op_sel_hi:[1,0]
	ds_read_b128 v[70:73], v15 offset:14336
	ds_read_b128 v[74:77], v15 offset:15360
	ds_read_b128 v[100:103], v15 offset:18432
	ds_read_b128 v[104:107], v15 offset:19456
	v_sub_f32_e32 v69, v69, v79
	v_sub_f32_e32 v68, v68, v79
	v_sub_f32_e32 v67, v67, v79
	s_waitcnt lgkmcnt(0)
; #define LAS __attribute__((address_space(3)))
; __device__ __forceinline__ void row_pass(const Params& P, int l, int mode, LAS float* pl) {
;     ...
;             for (int r = 0; r < 2; ++r) { const float mean = s[r] * (1.f / DM); const float var = fmaxf(q[r] * (1.f / DM) - mean * mean, 0.f); const float rstd = 1.f / sqrtf(var + LN_EPS);
; #pragma unroll
;                 for (int j = 0; j < 4; ++j) { const f32x4 g = *(const LAS f32x4*)(pl + 3072 + 4 * lane + 256 * j), bb = *(const LAS f32x4*)(pl + 4096 + 4 * lane + 256 * j); v[r][j] = (v[r][j] - mean) * rstd * g + bb; } }
;         }
;         if (mode != 0) {
; #pragma unroll
;         for (int r = 0; r < 2; ++r) if (ok[r]) {
; #pragma unroll
;             for (int j = 0; j < 4; ++j) __builtin_nontemporal_store(v[r][j], (f32x4*)(dst[r] + 4 * lane + 256 * j)); } }
;         if (make_h) {
;             float s[2], q[2];
; #pragma unroll
;             for (int r = 0; r < 2; ++r) { s[r] = 0.f; q[r] = 0.f;
; #pragma unroll
;                 for (int j = 0; j < 4; ++j) { s[r] += (v[r][j][0] + v[r][j][1]) + (v[r][j][2] + v[r][j][3]); const f32x4 sq = v[r][j] * v[r][j]; q[r] += (sq[0] + sq[1]) + (sq[2] + sq[3]); } }
	v_pk_fma_f32 v[54:55], v[70:71], v[108:109], v[100:101]
	v_pk_add_f32 v[108:109], v[114:115], v[192:193]
	v_sub_f32_e32 v66, v66, v79
	v_pk_mul_f32 v[108:109], v[108:109], s[10:11] op_sel_hi:[1,0]
	v_sub_f32_e32 v65, v65, v79
	v_fma_f32 v78, -v109, v109, v108
	v_max_f32_e32 v78, 0, v78
	v_add_f32_e32 v78, 0x358637bd, v78
	v_mul_f32_e32 v81, 0x4f800000, v78
	v_cmp_gt_f32_e32 vcc, s69, v78
	v_sub_f32_e32 v64, v64, v79
	v_sub_f32_e32 v63, v63, v79
	v_cndmask_b32_e32 v78, v78, v81, vcc
	v_sqrt_f32_e32 v81, v78
	v_sub_f32_e32 v62, v62, v79
	v_pk_mul_f32 v[66:67], v[66:67], v[0:1] op_sel_hi:[1,0]
	v_pk_mul_f32 v[68:69], v[68:69], v[0:1] op_sel_hi:[1,0]
	v_add_u32_e32 v79, -1, v81
	v_fma_f32 v99, -v79, v81, v78
	v_cmp_ge_f32_e64 s[0:1], 0, v99
	v_add_u32_e32 v99, 1, v81
	v_pk_mul_f32 v[62:63], v[62:63], v[0:1] op_sel_hi:[1,0]
	v_cndmask_b32_e64 v79, v81, v79, s[0:1]
	v_fma_f32 v81, -v99, v81, v78
	v_cmp_lt_f32_e64 s[0:1], 0, v81
	v_pk_mul_f32 v[64:65], v[64:65], v[0:1] op_sel_hi:[1,0]
	v_sub_f32_e32 v43, v43, v109
	v_cndmask_b32_e64 v79, v79, v99, s[0:1]
	v_mul_f32_e32 v81, 0x37800000, v79
	v_cndmask_b32_e32 v79, v79, v81, vcc
	v_cmp_class_f32_e32 vcc, v78, v217
	v_sub_f32_e32 v42, v42, v109
	v_sub_f32_e32 v53, v53, v109
	v_cndmask_b32_e32 v78, v79, v78, vcc
	v_div_scale_f32 v79, s[0:1], v78, v78, 1.0
	v_rcp_f32_e32 v81, v79
	v_sub_f32_e32 v52, v52, v109
	v_sub_f32_e32 v51, v51, v109
	v_sub_f32_e32 v50, v50, v109
	v_fma_f32 v0, -v79, v81, 1.0
	v_fmac_f32_e32 v81, v0, v81
	v_div_scale_f32 v0, vcc, 1.0, v78, 1.0
	v_mul_f32_e32 v99, v0, v81
	v_fma_f32 v108, -v79, v99, v0
	v_fmac_f32_e32 v99, v108, v81
	v_fma_f32 v0, -v79, v99, v0
	v_div_fmas_f32 v0, v0, v81, v99
	v_div_fixup_f32 v0, v0, v78, 1.0
	v_sub_f32_e32 v49, v49, v109
	v_sub_f32_e32 v48, v48, v109
	v_sub_f32_e32 v47, v47, v109
	v_sub_f32_e32 v46, v46, v109
	v_sub_f32_e32 v45, v45, v109
	v_sub_f32_e32 v44, v44, v109
	v_pk_mul_f32 v[42:43], v[42:43], v[0:1] op_sel_hi:[1,0]
	v_sub_f32_e32 v41, v41, v109
	v_sub_f32_e32 v40, v40, v109
	v_sub_f32_e32 v39, v39, v109
	v_sub_f32_e32 v38, v38, v109
	v_pk_mul_f32 v[50:51], v[50:51], v[0:1] op_sel_hi:[1,0]
	v_pk_mul_f32 v[52:53], v[52:53], v[0:1] op_sel_hi:[1,0]
	v_pk_mul_f32 v[46:47], v[46:47], v[0:1] op_sel_hi:[1,0]
	v_pk_mul_f32 v[48:49], v[48:49], v[0:1] op_sel_hi:[1,0]
	v_pk_mul_f32 v[44:45], v[44:45], v[0:1] op_sel_hi:[1,0]
	v_pk_fma_f32 v[42:43], v[70:71], v[42:43], v[100:101]
	v_pk_mul_f32 v[38:39], v[38:39], v[0:1] op_sel_hi:[1,0]
	v_pk_mul_f32 v[40:41], v[40:41], v[0:1] op_sel_hi:[1,0]
	v_cndmask_b32_e64 v70, 0, 1, s[16:17]
	v_pk_fma_f32 v[68:69], v[84:85], v[68:69], v[92:93]
	v_pk_fma_f32 v[66:67], v[82:83], v[66:67], v[90:91]
	v_pk_fma_f32 v[56:57], v[72:73], v[110:111], v[102:103]
	s_mov_b32 s2, 0x3a800000
	s_waitcnt lgkmcnt(0)
	v_pk_fma_f32 v[64:65], v[76:77], v[64:65], v[106:107]
	v_pk_fma_f32 v[62:63], v[74:75], v[62:63], v[104:105]
	v_pk_fma_f32 v[52:53], v[84:85], v[52:53], v[92:93]
	v_pk_fma_f32 v[50:51], v[82:83], v[50:51], v[90:91]
	v_pk_fma_f32 v[48:49], v[88:89], v[48:49], v[96:97]
	v_pk_fma_f32 v[46:47], v[86:87], v[46:47], v[94:95]
	v_pk_fma_f32 v[44:45], v[72:73], v[44:45], v[102:103]
	v_pk_fma_f32 v[40:41], v[76:77], v[40:41], v[106:107]
	v_pk_fma_f32 v[38:39], v[74:75], v[38:39], v[104:105]
	v_lshlrev_b32_e32 v0, 2, v14
	v_cmp_ne_u32_e64 s[10:11], 1, v70
	s_andn2_b64 vcc, exec, s[16:17]
	global_store_dwordx4 v0, v[66:69], s[22:23] nt
	global_store_dwordx4 v0, v[58:61], s[22:23] offset:1024 nt
	global_store_dwordx4 v0, v[54:57], s[22:23] offset:2048 nt
	global_store_dwordx4 v0, v[62:65], s[22:23] offset:3072 nt
	s_cbranch_vccnz .LBB0_1307
	s_and_b64 s[0:1], s[38:39], exec
	s_cselect_b32 s0, s25, s18
	s_ashr_i32 s1, s0, 31
	s_lshl_b64 s[0:1], s[0:1], 12
	s_add_u32 s0, s14, s0
	s_addc_u32 s1, s15, s1
	global_store_dwordx4 v0, v[50:53], s[0:1] nt
	global_store_dwordx4 v0, v[46:49], s[0:1] offset:1024 nt
	global_store_dwordx4 v0, v[42:45], s[0:1] offset:2048 nt
	global_store_dwordx4 v0, v[38:41], s[0:1] offset:3072 nt
.LBB0_1307:
	s_and_b64 vcc, exec, s[8:9]
	s_cbranch_vccnz .LBB0_1310
	v_pk_mul_f32 v[100:101], v[50:51], v[50:51]
	v_pk_mul_f32 v[96:97], v[52:53], v[52:53]
	v_pk_mul_f32 v[104:105], v[46:47], v[46:47]
	v_mov_b32_e32 v112, v100
	v_mov_b32_e32 v113, v46
	v_mov_b32_e32 v100, v101
	v_mov_b32_e32 v101, v47
	v_add_f32_e32 v93, v50, v51
	v_add_f32_e32 v95, v52, v53
	v_pk_mul_f32 v[102:103], v[48:49], v[48:49]
	v_pk_add_f32 v[100:101], v[112:113], v[100:101]
	v_mov_b32_e32 v112, v96
	v_mov_b32_e32 v113, v48
	v_mov_b32_e32 v96, v97
	v_mov_b32_e32 v97, v49
	v_mov_b32_e32 v92, v104
	v_mov_b32_e32 v94, v105
	v_add_f32_e32 v0, v102, v103
	v_pk_add_f32 v[96:97], v[112:113], v[96:97]
	v_pk_add_f32 v[92:93], v[92:93], v[94:95]
	v_pk_mul_f32 v[106:107], v[42:43], v[42:43]
	v_pk_add_f32 v[96:97], v[100:101], v[96:97]
	v_pk_add_f32 v[92:93], v[92:93], v[0:1]
	v_pk_mul_f32 v[102:103], v[44:45], v[44:45]
	v_pk_add_f32 v[92:93], v[96:97], v[92:93]
	v_mov_b32_e32 v94, v106
	v_mov_b32_e32 v95, v42
	v_mov_b32_e32 v96, v107
	v_mov_b32_e32 v97, v43
	v_pk_add_f32 v[94:95], v[94:95], v[96:97]
	v_mov_b32_e32 v96, v102
	v_mov_b32_e32 v97, v44
	v_mov_b32_e32 v100, v103
	v_mov_b32_e32 v101, v45
	v_pk_mul_f32 v[76:77], v[66:67], v[66:67]
	v_pk_add_f32 v[96:97], v[96:97], v[100:101]
	v_pk_mul_f32 v[74:75], v[68:69], v[68:69]
	v_pk_mul_f32 v[82:83], v[58:59], v[58:59]
	v_pk_add_f32 v[94:95], v[94:95], v[96:97]
	v_mov_b32_e32 v96, v76
	v_mov_b32_e32 v97, v58
	v_mov_b32_e32 v76, v77
	v_mov_b32_e32 v77, v59
	v_add_f32_e32 v71, v66, v67
	v_add_f32_e32 v73, v68, v69
	v_pk_mul_f32 v[78:79], v[60:61], v[60:61]
	v_pk_add_f32 v[76:77], v[96:97], v[76:77]
; #define LAS __attribute__((address_space(3)))
; __device__ __forceinline__ unsigned cvt_pk_bf16(float lo, float hi) { unsigned r; asm volatile("v_cvt_pk_bf16_f32 %0, %1, %2" : "=v"(r) : "v"(lo), "v"(hi)); return r; }
; __device__ __forceinline__ void row_pass(const Params& P, int l, int mode, LAS float* pl) {
;     ...
;         if (make_h) {
;             float s[2], q[2];
; #pragma unroll
;             for (int r = 0; r < 2; ++r) { s[r] = 0.f; q[r] = 0.f;
; #pragma unroll
;                 for (int j = 0; j < 4; ++j) { s[r] += (v[r][j][0] + v[r][j][1]) + (v[r][j][2] + v[r][j][3]); const f32x4 sq = v[r][j] * v[r][j]; q[r] += (sq[0] + sq[1]) + (sq[2] + sq[3]); } }
;             wave_sum2(s[0], s[1]); wave_sum2(q[0], q[1]);
; #pragma unroll
;             for (int r = 0; r < 2; ++r) if (ok[r]) { const float mean = s[r] * (1.f / DM); const float var = fmaxf(q[r] * (1.f / DM) - mean * mean, 0.f); const float rstd = 1.f / sqrtf(var + LN_EPS);
;                 const LAS float* mm = pl + 5120 + mv[r] * DM;
; #pragma unroll
;                 for (int j = 0; j < 4; ++j) { const f32x4 sh = *(const LAS f32x4*)(mm + 4 * lane + 256 * j), sc1 = *(const LAS f32x4*)(mm + 3072 + 4 * lane + 256 * j);
;                     const f32x4 hv = (v[r][j] - mean) * rstd * sc1 + sh; u32x2 o; o.x = cvt_pk_bf16(hv[0], hv[1]); o.y = cvt_pk_bf16(hv[2], hv[3]);
;                     *(u32x2*)(H + (size_t)row[r] * DM + 4 * lane + 256 * j) = o; } }
	v_mov_b32_e32 v96, v74
	v_mov_b32_e32 v97, v60
	v_mov_b32_e32 v74, v75
	v_mov_b32_e32 v75, v61
	v_mov_b32_e32 v70, v82
	v_mov_b32_e32 v72, v83
	v_add_f32_e32 v78, v78, v79
	v_pk_add_f32 v[74:75], v[96:97], v[74:75]
	v_pk_add_f32 v[70:71], v[70:71], v[72:73]
	v_mov_b32_e32 v79, v1
	v_pk_mul_f32 v[86:87], v[54:55], v[54:55]
	v_pk_add_f32 v[74:75], v[76:77], v[74:75]
	v_pk_add_f32 v[70:71], v[70:71], v[78:79]
	v_pk_mul_f32 v[84:85], v[56:57], v[56:57]
	v_pk_add_f32 v[70:71], v[74:75], v[70:71]
	v_mov_b32_e32 v72, v86
	v_mov_b32_e32 v73, v54
	v_mov_b32_e32 v74, v87
	v_mov_b32_e32 v75, v55
	v_pk_add_f32 v[72:73], v[72:73], v[74:75]
	v_mov_b32_e32 v74, v84
	v_mov_b32_e32 v75, v56
	v_mov_b32_e32 v76, v85
	v_mov_b32_e32 v77, v57
	v_pk_add_f32 v[74:75], v[74:75], v[76:77]
	v_pk_mul_f32 v[90:91], v[62:63], v[62:63]
	v_pk_add_f32 v[72:73], v[72:73], v[74:75]
	v_pk_mul_f32 v[88:89], v[64:65], v[64:65]
	v_pk_add_f32 v[70:71], v[72:73], v[70:71]
	v_mov_b32_e32 v72, v90
	v_mov_b32_e32 v73, v62
	v_mov_b32_e32 v74, v91
	v_mov_b32_e32 v75, v63
	v_pk_add_f32 v[72:73], v[72:73], v[74:75]
	v_mov_b32_e32 v74, v88
	v_mov_b32_e32 v75, v64
	v_mov_b32_e32 v76, v89
	v_mov_b32_e32 v77, v65
	v_pk_add_f32 v[74:75], v[74:75], v[76:77]
	v_pk_mul_f32 v[108:109], v[40:41], v[40:41]
	v_pk_add_f32 v[72:73], v[72:73], v[74:75]
	v_pk_mul_f32 v[110:111], v[38:39], v[38:39]
	v_pk_add_f32 v[70:71], v[72:73], v[70:71]
	s_nop 1
	v_mov_b32_dpp v73, v71 quad_perm:[1,0,3,2] row_mask:0xf bank_mask:0xf
	s_nop 1
	v_mov_b32_dpp v72, v70 quad_perm:[1,0,3,2] row_mask:0xf bank_mask:0xf
	v_pk_add_f32 v[92:93], v[94:95], v[92:93]
	v_mov_b32_e32 v94, v110
	v_mov_b32_e32 v95, v38
	v_mov_b32_e32 v74, v111
	s_waitcnt lgkmcnt(0)
	v_pk_add_f32 v[70:71], v[70:71], v[72:73]
	s_nop 1
	v_mov_b32_dpp v73, v71 quad_perm:[2,3,0,1] row_mask:0xf bank_mask:0xf
	s_nop 1
	v_mov_b32_dpp v72, v70 quad_perm:[2,3,0,1] row_mask:0xf bank_mask:0xf
	v_mov_b32_e32 v75, v39
	v_mov_b32_e32 v76, v108
	v_mov_b32_e32 v77, v40
	v_mov_b32_e32 v78, v109
	s_waitcnt lgkmcnt(0)
	v_pk_add_f32 v[70:71], v[70:71], v[72:73]
	s_nop 1
	v_mov_b32_dpp v73, v71 row_half_mirror row_mask:0xf bank_mask:0xf
	s_nop 1
	v_mov_b32_dpp v72, v70 row_half_mirror row_mask:0xf bank_mask:0xf
	v_mov_b32_e32 v79, v41
	v_pk_add_f32 v[74:75], v[94:95], v[74:75]
	v_pk_add_f32 v[76:77], v[76:77], v[78:79]
	s_ashr_i32 s21, s20, 31
	s_waitcnt lgkmcnt(0)
	v_pk_add_f32 v[70:71], v[70:71], v[72:73]
	s_nop 1
	v_mov_b32_dpp v73, v71 row_mirror row_mask:0xf bank_mask:0xf
	s_nop 1
	v_mov_b32_dpp v72, v70 row_mirror row_mask:0xf bank_mask:0xf
	v_pk_add_f32 v[74:75], v[74:75], v[76:77]
	s_waitcnt lgkmcnt(0)
	v_pk_add_f32 v[70:71], v[70:71], v[72:73]
	v_pk_add_f32 v[74:75], v[74:75], v[92:93]
	s_nop 1
	v_mov_b32_dpp v77, v75 quad_perm:[1,0,3,2] row_mask:0xf bank_mask:0xf
	s_nop 1
	v_mov_b32_dpp v76, v74 quad_perm:[1,0,3,2] row_mask:0xf bank_mask:0xf
	v_mov_b32_e32 v72, v70
	v_mov_b32_e32 v73, v71
	v_mov_b32_e32 v192, v70
	v_mov_b32_e32 v193, v71
	s_nop 1
	v_permlane16_swap_b32_e32 v72, v192
	v_permlane16_swap_b32_e32 v73, v193
	s_waitcnt lgkmcnt(0)
	v_pk_add_f32 v[74:75], v[74:75], v[76:77]
	s_nop 1
	v_mov_b32_dpp v77, v75 quad_perm:[2,3,0,1] row_mask:0xf bank_mask:0xf
	s_nop 1
	v_mov_b32_dpp v76, v74 quad_perm:[2,3,0,1] row_mask:0xf bank_mask:0xf
	s_waitcnt lgkmcnt(0)
	v_pk_add_f32 v[70:71], v[72:73], v[192:193]
	v_mov_b32_e32 v72, v70
	v_mov_b32_e32 v73, v71
	v_mov_b32_e32 v192, v70
	v_mov_b32_e32 v193, v71
	s_nop 1
	v_permlane32_swap_b32_e32 v72, v192
	v_permlane32_swap_b32_e32 v73, v193
	s_waitcnt lgkmcnt(0)
	v_pk_add_f32 v[74:75], v[74:75], v[76:77]
	s_nop 1
	v_mov_b32_dpp v77, v75 row_half_mirror row_mask:0xf bank_mask:0xf
	s_nop 1
	v_mov_b32_dpp v76, v74 row_half_mirror row_mask:0xf bank_mask:0xf
	s_waitcnt lgkmcnt(0)
	v_pk_add_f32 v[70:71], v[72:73], v[192:193]
	s_waitcnt lgkmcnt(0)
	v_pk_add_f32 v[74:75], v[74:75], v[76:77]
	v_pk_mul_f32 v[78:79], v[70:71], s[2:3] op_sel_hi:[1,0]
	s_nop 1
	v_mov_b32_dpp v77, v75 row_mirror row_mask:0xf bank_mask:0xf
	v_fma_f32 v0, -v79, v79, v78
	v_max_f32_e32 v0, 0, v0
	v_add_f32_e32 v0, 0x358637bd, v0
	v_mul_f32_e32 v70, 0x4f800000, v0
	v_cmp_gt_f32_e32 vcc, s69, v0
	s_nop 1
	v_mov_b32_dpp v76, v74 row_mirror row_mask:0xf bank_mask:0xf
	v_sub_f32_e32 v67, v67, v79
	v_cndmask_b32_e32 v0, v0, v70, vcc
	v_sqrt_f32_e32 v78, v0
	v_sub_f32_e32 v66, v66, v79
	s_waitcnt lgkmcnt(0)
	v_pk_add_f32 v[70:71], v[74:75], v[76:77]
	v_sub_f32_e32 v69, v69, v79
	v_add_u32_e32 v74, -1, v78
	v_fma_f32 v75, -v74, v78, v0
	v_cmp_ge_f32_e64 s[0:1], 0, v75
	v_add_u32_e32 v75, 1, v78
	v_fma_f32 v76, -v75, v78, v0
	v_cndmask_b32_e64 v74, v78, v74, s[0:1]
	v_cmp_lt_f32_e64 s[0:1], 0, v76
	v_sub_f32_e32 v68, v68, v79
	v_sub_f32_e32 v59, v59, v79
	v_cndmask_b32_e64 v74, v74, v75, s[0:1]
	v_mul_f32_e32 v75, 0x37800000, v74
	v_cndmask_b32_e32 v74, v74, v75, vcc
	v_cmp_class_f32_e32 vcc, v0, v217
	v_sub_f32_e32 v58, v58, v79
	v_sub_f32_e32 v61, v61, v79
	v_cndmask_b32_e32 v0, v74, v0, vcc
	v_div_scale_f32 v74, s[0:1], v0, v0, 1.0
	v_rcp_f32_e32 v75, v74
	s_lshl_b64 s[0:1], s[20:21], 11
	v_sub_f32_e32 v60, v60, v79
	v_fma_f32 v76, -v74, v75, 1.0
	v_fmac_f32_e32 v75, v76, v75
	v_div_scale_f32 v76, vcc, 1.0, v0, 1.0
	v_mul_f32_e32 v77, v76, v75
	v_fma_f32 v78, -v74, v77, v76
	v_fmac_f32_e32 v77, v78, v75
	v_fma_f32 v74, -v74, v77, v76
	v_div_fmas_f32 v74, v74, v75, v77
	v_div_fixup_f32 v0, v74, v0, 1.0
	ds_read_b128 v[74:77], v98 offset:20480
	ds_read_b128 v[82:85], v98 offset:32768
	v_pk_mul_f32 v[66:67], v[66:67], v[0:1] op_sel_hi:[1,0]
	v_pk_mul_f32 v[68:69], v[68:69], v[0:1] op_sel_hi:[1,0]
	v_pk_mul_f32 v[58:59], v[58:59], v[0:1] op_sel_hi:[1,0]
	v_pk_mul_f32 v[60:61], v[60:61], v[0:1] op_sel_hi:[1,0]
	s_waitcnt lgkmcnt(0)
; #define LAS __attribute__((address_space(3)))
; __device__ __forceinline__ unsigned cvt_pk_bf16(float lo, float hi) { unsigned r; asm volatile("v_cvt_pk_bf16_f32 %0, %1, %2" : "=v"(r) : "v"(lo), "v"(hi)); return r; }
; __device__ __forceinline__ void row_pass(const Params& P, int l, int mode, LAS float* pl) {
;     ...
;             wave_sum2(s[0], s[1]); wave_sum2(q[0], q[1]);
; #pragma unroll
;             for (int r = 0; r < 2; ++r) if (ok[r]) { const float mean = s[r] * (1.f / DM); const float var = fmaxf(q[r] * (1.f / DM) - mean * mean, 0.f); const float rstd = 1.f / sqrtf(var + LN_EPS);
;                 const LAS float* mm = pl + 5120 + mv[r] * DM;
; #pragma unroll
;                 for (int j = 0; j < 4; ++j) { const f32x4 sh = *(const LAS f32x4*)(mm + 4 * lane + 256 * j), sc1 = *(const LAS f32x4*)(mm + 3072 + 4 * lane + 256 * j);
;                     const f32x4 hv = (v[r][j] - mean) * rstd * sc1 + sh; u32x2 o; o.x = cvt_pk_bf16(hv[0], hv[1]); o.y = cvt_pk_bf16(hv[2], hv[3]);
;                     *(u32x2*)(H + (size_t)row[r] * DM + 4 * lane + 256 * j) = o; } }
	v_pk_fma_f32 v[66:67], v[82:83], v[66:67], v[74:75]
	v_lshl_add_u64 v[82:83], v[146:147], 0, s[0:1]
	v_pk_fma_f32 v[68:69], v[84:85], v[68:69], v[76:77]
	v_cvt_pk_bf16_f32 v66, v66, v67
	v_mov_b32_e32 v72, v70
	v_mov_b32_e32 v73, v71
	v_mov_b32_e32 v192, v70
	v_mov_b32_e32 v193, v71
	s_nop 1
	v_permlane16_swap_b32_e32 v72, v192
	v_permlane16_swap_b32_e32 v73, v193
	v_cvt_pk_bf16_f32 v67, v68, v69
	global_store_dwordx2 v[82:83], v[66:67], off
	ds_read_b128 v[66:69], v98 offset:21504
	ds_read_b128 v[74:77], v98 offset:33792
	v_sub_f32_e32 v55, v55, v79
	v_sub_f32_e32 v54, v54, v79
	v_sub_f32_e32 v57, v57, v79
	v_sub_f32_e32 v56, v56, v79
	s_waitcnt lgkmcnt(0)
	v_pk_fma_f32 v[58:59], v[74:75], v[58:59], v[66:67]
	v_pk_fma_f32 v[60:61], v[76:77], v[60:61], v[68:69]
	v_cvt_pk_bf16_f32 v58, v58, v59
	v_pk_mul_f32 v[54:55], v[54:55], v[0:1] op_sel_hi:[1,0]
	v_cvt_pk_bf16_f32 v59, v60, v61
	global_store_dwordx2 v[82:83], v[58:59], off offset:512
	ds_read_b128 v[58:61], v98 offset:22528
	ds_read_b128 v[66:69], v98 offset:34816
	v_pk_mul_f32 v[56:57], v[56:57], v[0:1] op_sel_hi:[1,0]
	v_pk_add_f32 v[70:71], v[72:73], v[192:193]
	v_mov_b32_e32 v72, v70
	v_mov_b32_e32 v73, v71
	v_mov_b32_e32 v192, v70
	v_mov_b32_e32 v193, v71
	s_nop 1
	v_permlane32_swap_b32_e32 v72, v192
	v_permlane32_swap_b32_e32 v73, v193
	s_waitcnt lgkmcnt(0)
	v_pk_fma_f32 v[54:55], v[54:55], v[66:67], v[58:59]
	v_pk_fma_f32 v[56:57], v[56:57], v[68:69], v[60:61]
	v_cvt_pk_bf16_f32 v54, v54, v55
	v_sub_f32_e32 v63, v63, v79
	v_cvt_pk_bf16_f32 v55, v56, v57
	global_store_dwordx2 v[82:83], v[54:55], off offset:1024
	ds_read_b128 v[54:57], v98 offset:23552
	ds_read_b128 v[58:61], v98 offset:35840
	v_sub_f32_e32 v62, v62, v79
	v_sub_f32_e32 v65, v65, v79
	v_sub_f32_e32 v64, v64, v79
	v_pk_mul_f32 v[62:63], v[62:63], v[0:1] op_sel_hi:[1,0]
	v_pk_mul_f32 v[64:65], v[64:65], v[0:1] op_sel_hi:[1,0]
	s_waitcnt lgkmcnt(0)
	v_pk_fma_f32 v[54:55], v[62:63], v[58:59], v[54:55]
	s_and_b64 vcc, exec, s[10:11]
	v_pk_fma_f32 v[56:57], v[64:65], v[60:61], v[56:57]
	v_cvt_pk_bf16_f32 v54, v54, v55
	s_nop 0
	v_cvt_pk_bf16_f32 v55, v56, v57
	global_store_dwordx2 v[82:83], v[54:55], off offset:1536
	s_cbranch_vccnz .LBB0_1310
	v_pk_add_f32 v[54:55], v[72:73], v[192:193]
	s_ashr_i32 s19, s18, 31
	v_pk_mul_f32 v[62:63], v[54:55], s[2:3] op_sel_hi:[1,0]
	s_nop 0
	v_fma_f32 v0, -v63, v63, v62
	v_max_f32_e32 v0, 0, v0
	v_add_f32_e32 v0, 0x358637bd, v0
	v_mul_f32_e32 v54, 0x4f800000, v0
	v_cmp_gt_f32_e32 vcc, s69, v0
	v_sub_f32_e32 v51, v51, v63
	v_sub_f32_e32 v50, v50, v63
	v_cndmask_b32_e32 v0, v0, v54, vcc
	v_sqrt_f32_e32 v54, v0
	v_sub_f32_e32 v53, v53, v63
	v_sub_f32_e32 v52, v52, v63
	v_sub_f32_e32 v47, v47, v63
	v_add_u32_e32 v55, -1, v54
	v_fma_f32 v57, -v55, v54, v0
	v_add_u32_e32 v56, 1, v54
	v_cmp_ge_f32_e64 s[0:1], 0, v57
	v_sub_f32_e32 v46, v46, v63
	v_sub_f32_e32 v49, v49, v63
	v_cndmask_b32_e64 v55, v54, v55, s[0:1]
	v_fma_f32 v54, -v56, v54, v0
	v_cmp_lt_f32_e64 s[0:1], 0, v54
	v_sub_f32_e32 v48, v48, v63
	v_sub_f32_e32 v43, v43, v63
	v_cndmask_b32_e64 v54, v55, v56, s[0:1]
	v_mul_f32_e32 v55, 0x37800000, v54
	v_cndmask_b32_e32 v54, v54, v55, vcc
	v_cmp_class_f32_e32 vcc, v0, v217
	v_sub_f32_e32 v42, v42, v63
	v_sub_f32_e32 v45, v45, v63
	v_cndmask_b32_e32 v0, v54, v0, vcc
	v_div_scale_f32 v54, s[0:1], v0, v0, 1.0
	v_rcp_f32_e32 v55, v54
	s_lshl_b64 s[0:1], s[18:19], 11
	v_sub_f32_e32 v44, v44, v63
	v_sub_f32_e32 v39, v39, v63
	v_fma_f32 v56, -v54, v55, 1.0
	v_fmac_f32_e32 v55, v56, v55
	v_div_scale_f32 v56, vcc, 1.0, v0, 1.0
	v_mul_f32_e32 v57, v56, v55
	v_fma_f32 v58, -v54, v57, v56
	v_fmac_f32_e32 v57, v58, v55
	v_fma_f32 v54, -v54, v57, v56
	v_div_fmas_f32 v54, v54, v55, v57
	v_div_fixup_f32 v0, v54, v0, 1.0
	ds_read_b128 v[54:57], v80 offset:20480
	ds_read_b128 v[58:61], v80 offset:32768
	v_pk_mul_f32 v[50:51], v[50:51], v[0:1] op_sel_hi:[1,0]
	v_pk_mul_f32 v[52:53], v[52:53], v[0:1] op_sel_hi:[1,0]
	v_pk_mul_f32 v[46:47], v[46:47], v[0:1] op_sel_hi:[1,0]
	v_pk_mul_f32 v[48:49], v[48:49], v[0:1] op_sel_hi:[1,0]
	s_waitcnt lgkmcnt(0)
	v_pk_fma_f32 v[50:51], v[50:51], v[58:59], v[54:55]
	v_lshl_add_u64 v[58:59], v[146:147], 0, s[0:1]
	v_pk_fma_f32 v[52:53], v[52:53], v[60:61], v[56:57]
	v_cvt_pk_bf16_f32 v50, v50, v51
	v_pk_mul_f32 v[42:43], v[42:43], v[0:1] op_sel_hi:[1,0]
	v_cvt_pk_bf16_f32 v51, v52, v53
	global_store_dwordx2 v[58:59], v[50:51], off
	ds_read_b128 v[50:53], v80 offset:21504
	ds_read_b128 v[54:57], v80 offset:33792
	v_pk_mul_f32 v[44:45], v[44:45], v[0:1] op_sel_hi:[1,0]
	v_sub_f32_e32 v38, v38, v63
	v_sub_f32_e32 v41, v41, v63
	v_sub_f32_e32 v40, v40, v63
	s_waitcnt lgkmcnt(0)
	v_pk_fma_f32 v[46:47], v[46:47], v[54:55], v[50:51]
	v_pk_fma_f32 v[48:49], v[48:49], v[56:57], v[52:53]
	v_cvt_pk_bf16_f32 v46, v46, v47
	v_pk_mul_f32 v[38:39], v[38:39], v[0:1] op_sel_hi:[1,0]
	v_cvt_pk_bf16_f32 v47, v48, v49
	global_store_dwordx2 v[58:59], v[46:47], off offset:512
	ds_read_b128 v[46:49], v80 offset:22528
	ds_read_b128 v[50:53], v80 offset:34816
	v_pk_mul_f32 v[40:41], v[40:41], v[0:1] op_sel_hi:[1,0]
	s_waitcnt lgkmcnt(0)
	v_pk_fma_f32 v[42:43], v[42:43], v[50:51], v[46:47]
	v_pk_fma_f32 v[44:45], v[44:45], v[52:53], v[48:49]
	v_cvt_pk_bf16_f32 v42, v42, v43
	s_nop 0
	v_cvt_pk_bf16_f32 v43, v44, v45
	global_store_dwordx2 v[58:59], v[42:43], off offset:1024
	ds_read_b128 v[42:45], v80 offset:23552
	ds_read_b128 v[46:49], v80 offset:35840
	s_waitcnt lgkmcnt(0)
	v_pk_fma_f32 v[38:39], v[38:39], v[46:47], v[42:43]
	v_pk_fma_f32 v[40:41], v[40:41], v[48:49], v[44:45]
	v_cvt_pk_bf16_f32 v38, v38, v39
	s_nop 0
	v_cvt_pk_bf16_f32 v39, v40, v41
	global_store_dwordx2 v[58:59], v[38:39], off offset:1536
